# K-loop load segments reordered: LDS-DMA tile loads issued before the ds_read fragment reads (more latency budget), on top of the rewritten FFN-up epilogue
# baseline (speedup 1.0000x reference)
; #define PG8_STAGE(bufoff, gbase, voff) do { _Pragma("unroll") for (int _i = 0; _i < 2; ++_i) \
;         __builtin_amdgcn_global_load_lds((const unsigned*)((const char*)(gbase) + (voff)[_i]), (PG8_LAS unsigned*)(lds + (bufoff) + ldsw + _i * 8192), 16, 0, 0); } while (0)
; #define PG8_LDA(dst, b, h) do { _Pragma("unroll") for (int m = 0; m < 4; ++m) _Pragma("unroll") for (int k = 0; k < 2; ++k) dst[m][k] = *(const PG8_LAS bf16x8*)(lds + PG8_SA(b, h) + aoff + m * 2048 + k * 1024); } while (0)
; #define PG8_LDB(dst, b, h) do { _Pragma("unroll") for (int n = 0; n < 2; ++n) _Pragma("unroll") for (int k = 0; k < 2; ++k) dst[n][k] = *(const PG8_LAS bf16x8*)(lds + PG8_SB(b, h) + boff + n * 2048 + k * 1024); } while (0)
; #define PG8_MMA(ai, bj, At, Bt) do { __builtin_amdgcn_s_setprio(1); _Pragma("unroll") for (int m = 0; m < 4; ++m) _Pragma("unroll") for (int n = 0; n < 2; ++n) _Pragma("unroll") for (int k = 0; k < 2; ++k) \
;         acc[ai][bj][m][n] = __builtin_amdgcn_mfma_f32_16x16x32_bf16(Bt[n][k], At[m][k], acc[ai][bj][m][n], 0, 0, 0); __builtin_amdgcn_s_setprio(0); } while (0)
; #define PG8_WAIT_V(n) asm volatile("s_waitcnt vmcnt(" #n ")" ::: "memory")
; #define PG8_WAIT_L(n) asm volatile("s_waitcnt lgkmcnt(" #n ")" ::: "memory")
; #define PG8_BAR __builtin_amdgcn_s_barrier()
; #define PG8_SCHED __builtin_amdgcn_sched_barrier(0)
; template <class Epi, class Sched, bool ALIGN_EPI = false, bool SP2 = false>
; __device__ __forceinline__ void gemm_phase(PG8_LAS unsigned char* lds, const Gemm g, const Sched& S, const Epi& E) {
;     ...
;             PG8_LDB(B0, 0, 0); PG8_LDB(B1, 0, 1); PG8_SCHED; PG8_LDA(At, 0, 0); PG8_STAGE(PG8_SA(1, 1), a1 + hstep, voffA);
;             PG8_WAIT_V(8); PG8_WAIT_L(0); PG8_BAR; PG8_MMA(0, 0, At, B0); PG8_MMA(0, 1, At, B1); PG8_BAR; PG8_SCHED;
;             PG8_LDA(At, 0, 1); PG8_STAGE(PG8_SB(0, 0), b2, voffB); PG8_STAGE(PG8_SB(0, 1), b2 + hstep, voffB); PG8_STAGE(PG8_SA(0, 0), a2, voffA);
;             PG8_WAIT_V(8); PG8_WAIT_L(0); PG8_BAR; PG8_MMA(1, 0, At, B0); PG8_MMA(1, 1, At, B1); PG8_BAR; PG8_SCHED;
.LBB0_317:
	s_add_u32 s20, s8, 0xfffc0080
	s_addc_u32 s21, s9, -1
	s_add_i32 s37, 0, 0x10000
	s_cmp_eq_u32 s55, 12
	s_cselect_b32 s47, s41, s21
	s_cselect_b32 s46, s51, s20
	s_cselect_b32 s21, s27, s54
	s_cselect_b32 s20, s52, s53
	s_add_i32 s58, 0, 0x14000
	v_lshl_add_u64 v[146:147], s[8:9], 0, v[136:137]
	s_add_i32 m0, s18, 0xc000
	s_nop 0
	global_load_lds_dwordx4 v[146:147], off
	v_lshl_add_u64 v[146:147], s[8:9], 0, v[138:139]
	s_add_i32 m0, s18, 0xe000
	s_nop 0
	global_load_lds_dwordx4 v[146:147], off
	v_add_u32_e32 v144, s37, v149
	ds_read_b128 v[140:143], v144
	ds_read_b128 v[158:161], v144 offset:1024
	ds_read_b128 v[162:165], v144 offset:2048
	ds_read_b128 v[166:169], v144 offset:3072
	v_add_u32_e32 v144, s58, v149
	ds_read_b128 v[170:173], v144
	ds_read_b128 v[174:177], v144 offset:1024
	ds_read_b128 v[178:181], v144 offset:2048
	ds_read_b128 v[182:185], v144 offset:3072
	ds_read_b128 v[186:189], v157
	ds_read_b128 v[190:193], v157 offset:1024
	ds_read_b128 v[204:207], v157 offset:2048
	ds_read_b128 v[208:211], v157 offset:3072
	ds_read_b128 v[212:215], v157 offset:4096
	ds_read_b128 v[216:219], v157 offset:5120
	ds_read_b128 v[220:223], v157 offset:6144
	ds_read_b128 v[224:227], v157 offset:7168
	s_waitcnt vmcnt(8)
	s_waitcnt lgkmcnt(0)
	s_barrier
	s_setprio 1
	s_waitcnt lgkmcnt(0)
	v_mfma_f32_16x16x32_bf16 v[126:129], v[140:143], v[186:189], v[126:129]
	v_mfma_f32_16x16x32_bf16 v[122:125], v[162:165], v[186:189], v[122:125]
	v_mfma_f32_16x16x32_bf16 v[110:113], v[140:143], v[204:207], v[110:113]
	v_mfma_f32_16x16x32_bf16 v[106:109], v[162:165], v[204:207], v[106:109]
	v_mfma_f32_16x16x32_bf16 v[94:97], v[140:143], v[212:215], v[94:97]
	v_mfma_f32_16x16x32_bf16 v[90:93], v[162:165], v[212:215], v[90:93]
	v_mfma_f32_16x16x32_bf16 v[78:81], v[140:143], v[220:223], v[78:81]
	v_mfma_f32_16x16x32_bf16 v[74:77], v[162:165], v[220:223], v[74:77]
	v_mfma_f32_16x16x32_bf16 v[126:129], v[158:161], v[190:193], v[126:129]
	v_mfma_f32_16x16x32_bf16 v[122:125], v[166:169], v[190:193], v[122:125]
	v_mfma_f32_16x16x32_bf16 v[110:113], v[158:161], v[208:211], v[110:113]
	v_mfma_f32_16x16x32_bf16 v[106:109], v[166:169], v[208:211], v[106:109]
	v_mfma_f32_16x16x32_bf16 v[94:97], v[158:161], v[216:219], v[94:97]
	v_mfma_f32_16x16x32_bf16 v[90:93], v[166:169], v[216:219], v[90:93]
	v_mfma_f32_16x16x32_bf16 v[78:81], v[158:161], v[224:227], v[78:81]
	v_mfma_f32_16x16x32_bf16 v[74:77], v[166:169], v[224:227], v[74:77]
	s_setprio 0
	s_setprio 1
	v_mfma_f32_16x16x32_bf16 v[118:121], v[170:173], v[186:189], v[118:121]
	v_mfma_f32_16x16x32_bf16 v[114:117], v[178:181], v[186:189], v[114:117]
	v_mfma_f32_16x16x32_bf16 v[102:105], v[170:173], v[204:207], v[102:105]
	v_mfma_f32_16x16x32_bf16 v[98:101], v[178:181], v[204:207], v[98:101]
	v_mfma_f32_16x16x32_bf16 v[86:89], v[170:173], v[212:215], v[86:89]
	v_mfma_f32_16x16x32_bf16 v[82:85], v[178:181], v[212:215], v[82:85]
	v_mfma_f32_16x16x32_bf16 v[70:73], v[170:173], v[220:223], v[70:73]
	v_mfma_f32_16x16x32_bf16 v[66:69], v[178:181], v[220:223], v[66:69]
	v_mfma_f32_16x16x32_bf16 v[118:121], v[174:177], v[190:193], v[118:121]
	v_mfma_f32_16x16x32_bf16 v[114:117], v[182:185], v[190:193], v[114:117]
	v_mfma_f32_16x16x32_bf16 v[102:105], v[174:177], v[208:211], v[102:105]
	v_mfma_f32_16x16x32_bf16 v[98:101], v[182:185], v[208:211], v[98:101]
	v_mfma_f32_16x16x32_bf16 v[86:89], v[174:177], v[216:219], v[86:89]
	v_mfma_f32_16x16x32_bf16 v[82:85], v[182:185], v[216:219], v[82:85]
	v_mfma_f32_16x16x32_bf16 v[70:73], v[174:177], v[224:227], v[70:73]
	v_mfma_f32_16x16x32_bf16 v[66:69], v[182:185], v[224:227], v[66:69]
	s_setprio 0
	s_barrier
	s_add_i32 s37, s37, s16
	v_lshl_add_u64 v[146:147], s[20:21], 0, v[0:1]
	s_mov_b32 m0, s37
	s_nop 0
	global_load_lds_dwordx4 v[146:147], off
	s_add_i32 m0, s37, 0x2000
	s_add_u32 s56, s20, 0x40000
	v_lshl_add_u64 v[150:151], s[20:21], 0, v[130:131]
	s_addc_u32 s57, s21, 0
	s_add_i32 s37, s58, s16
	global_load_lds_dwordx4 v[150:151], off
	v_lshl_add_u64 v[154:155], s[56:57], 0, v[0:1]
	s_mov_b32 m0, s37
	v_lshl_add_u64 v[228:229], s[46:47], 0, v[132:133]
	global_load_lds_dwordx4 v[154:155], off
	v_lshl_add_u64 v[154:155], s[56:57], 0, v[130:131]
	s_add_i32 m0, s37, 0x2000
	s_nop 0
	global_load_lds_dwordx4 v[154:155], off
	v_lshl_add_u64 v[154:155], s[46:47], 0, v[134:135]
	s_mov_b32 m0, s18
	s_nop 0
	global_load_lds_dwordx4 v[154:155], off
	s_mov_b32 m0, s19
	s_nop 0
	global_load_lds_dwordx4 v[228:229], off
	ds_read_b128 v[186:189], v157 offset:16384
	ds_read_b128 v[190:193], v157 offset:17408
	ds_read_b128 v[204:207], v157 offset:18432
	ds_read_b128 v[208:211], v157 offset:19456
	ds_read_b128 v[212:215], v157 offset:20480
	ds_read_b128 v[216:219], v157 offset:21504
	ds_read_b128 v[220:223], v157 offset:22528
	ds_read_b128 v[224:227], v157 offset:23552
	s_waitcnt vmcnt(8)
	s_waitcnt lgkmcnt(0)
	s_barrier
; #define PG8_STAGE(bufoff, gbase, voff) do { _Pragma("unroll") for (int _i = 0; _i < 2; ++_i) \
;         __builtin_amdgcn_global_load_lds((const unsigned*)((const char*)(gbase) + (voff)[_i]), (PG8_LAS unsigned*)(lds + (bufoff) + ldsw + _i * 8192), 16, 0, 0); } while (0)
; #define PG8_LDA(dst, b, h) do { _Pragma("unroll") for (int m = 0; m < 4; ++m) _Pragma("unroll") for (int k = 0; k < 2; ++k) dst[m][k] = *(const PG8_LAS bf16x8*)(lds + PG8_SA(b, h) + aoff + m * 2048 + k * 1024); } while (0)
; #define PG8_LDB(dst, b, h) do { _Pragma("unroll") for (int n = 0; n < 2; ++n) _Pragma("unroll") for (int k = 0; k < 2; ++k) dst[n][k] = *(const PG8_LAS bf16x8*)(lds + PG8_SB(b, h) + boff + n * 2048 + k * 1024); } while (0)
; #define PG8_MMA(ai, bj, At, Bt) do { __builtin_amdgcn_s_setprio(1); _Pragma("unroll") for (int m = 0; m < 4; ++m) _Pragma("unroll") for (int n = 0; n < 2; ++n) _Pragma("unroll") for (int k = 0; k < 2; ++k) \
;         acc[ai][bj][m][n] = __builtin_amdgcn_mfma_f32_16x16x32_bf16(Bt[n][k], At[m][k], acc[ai][bj][m][n], 0, 0, 0); __builtin_amdgcn_s_setprio(0); } while (0)
; #define PG8_WAIT_V(n) asm volatile("s_waitcnt vmcnt(" #n ")" ::: "memory")
; #define PG8_WAIT_L(n) asm volatile("s_waitcnt lgkmcnt(" #n ")" ::: "memory")
; #define PG8_BAR __builtin_amdgcn_s_barrier()
; #define PG8_SCHED __builtin_amdgcn_sched_barrier(0)
; template <class Epi, class Sched, bool ALIGN_EPI = false, bool SP2 = false>
; __device__ __forceinline__ void gemm_phase(PG8_LAS unsigned char* lds, const Gemm g, const Sched& S, const Epi& E) {
;     ...
;             PG8_WAIT_V(8); PG8_WAIT_L(0); PG8_BAR; PG8_MMA(1, 0, At, B0); PG8_MMA(1, 1, At, B1); PG8_BAR; PG8_SCHED;
;             PG8_LDB(B0, 1, 0); PG8_LDB(B1, 1, 1); PG8_SCHED; PG8_LDA(At, 1, 0); PG8_STAGE(PG8_SA(0, 1), a2 + hstep, voffA);
;             PG8_WAIT_V(8); PG8_WAIT_L(0); PG8_BAR; PG8_MMA(0, 0, At, B0); PG8_MMA(0, 1, At, B1); PG8_BAR; PG8_SCHED;
	s_setprio 1
	s_waitcnt lgkmcnt(0)
	v_mfma_f32_16x16x32_bf16 v[62:65], v[140:143], v[186:189], v[62:65]
	v_mfma_f32_16x16x32_bf16 v[58:61], v[162:165], v[186:189], v[58:61]
	v_mfma_f32_16x16x32_bf16 v[46:49], v[140:143], v[204:207], v[46:49]
	v_mfma_f32_16x16x32_bf16 v[42:45], v[162:165], v[204:207], v[42:45]
	v_mfma_f32_16x16x32_bf16 v[30:33], v[140:143], v[212:215], v[30:33]
	v_mfma_f32_16x16x32_bf16 v[26:29], v[162:165], v[212:215], v[26:29]
	v_mfma_f32_16x16x32_bf16 v[14:17], v[140:143], v[220:223], v[14:17]
	v_mfma_f32_16x16x32_bf16 v[10:13], v[162:165], v[220:223], v[10:13]
	v_mfma_f32_16x16x32_bf16 v[62:65], v[158:161], v[190:193], v[62:65]
	v_mfma_f32_16x16x32_bf16 v[58:61], v[166:169], v[190:193], v[58:61]
	v_mfma_f32_16x16x32_bf16 v[46:49], v[158:161], v[208:211], v[46:49]
	v_mfma_f32_16x16x32_bf16 v[42:45], v[166:169], v[208:211], v[42:45]
	v_mfma_f32_16x16x32_bf16 v[30:33], v[158:161], v[216:219], v[30:33]
	v_mfma_f32_16x16x32_bf16 v[26:29], v[166:169], v[216:219], v[26:29]
	v_mfma_f32_16x16x32_bf16 v[14:17], v[158:161], v[224:227], v[14:17]
	v_mfma_f32_16x16x32_bf16 v[10:13], v[166:169], v[224:227], v[10:13]
	s_setprio 0
	s_setprio 1
	v_mfma_f32_16x16x32_bf16 v[54:57], v[170:173], v[186:189], v[54:57]
	v_mfma_f32_16x16x32_bf16 v[50:53], v[178:181], v[186:189], v[50:53]
	v_mfma_f32_16x16x32_bf16 v[38:41], v[170:173], v[204:207], v[38:41]
	v_mfma_f32_16x16x32_bf16 v[34:37], v[178:181], v[204:207], v[34:37]
	v_mfma_f32_16x16x32_bf16 v[22:25], v[170:173], v[212:215], v[22:25]
	v_mfma_f32_16x16x32_bf16 v[18:21], v[178:181], v[212:215], v[18:21]
	v_mfma_f32_16x16x32_bf16 v[6:9], v[170:173], v[220:223], v[6:9]
	v_mfma_f32_16x16x32_bf16 v[2:5], v[178:181], v[220:223], v[2:5]
	v_mfma_f32_16x16x32_bf16 v[54:57], v[174:177], v[190:193], v[54:57]
	v_mfma_f32_16x16x32_bf16 v[50:53], v[182:185], v[190:193], v[50:53]
	v_mfma_f32_16x16x32_bf16 v[38:41], v[174:177], v[208:211], v[38:41]
	v_mfma_f32_16x16x32_bf16 v[34:37], v[182:185], v[208:211], v[34:37]
	v_mfma_f32_16x16x32_bf16 v[22:25], v[174:177], v[216:219], v[22:25]
	v_mfma_f32_16x16x32_bf16 v[18:21], v[182:185], v[216:219], v[18:21]
	v_mfma_f32_16x16x32_bf16 v[6:9], v[174:177], v[224:227], v[6:9]
	v_mfma_f32_16x16x32_bf16 v[2:5], v[182:185], v[224:227], v[2:5]
	s_setprio 0
	s_barrier
	s_add_i32 s37, 0, 0x18000
	s_add_i32 s56, 0, 0x1c000
	s_add_u32 s46, s46, 0x40000
	s_addc_u32 s47, s47, 0
	s_mov_b32 m0, s33
	v_lshl_add_u64 v[230:231], s[46:47], 0, v[134:135]
	global_load_lds_dwordx4 v[230:231], off
	v_lshl_add_u64 v[230:231], s[46:47], 0, v[132:133]
	s_mov_b32 m0, s34
	s_nop 0
	global_load_lds_dwordx4 v[230:231], off
	v_add_u32_e32 v144, s37, v149
	ds_read_b128 v[140:143], v144
	ds_read_b128 v[158:161], v144 offset:1024
	ds_read_b128 v[162:165], v144 offset:2048
	ds_read_b128 v[166:169], v144 offset:3072
	v_add_u32_e32 v144, s56, v149
	ds_read_b128 v[170:173], v144
	ds_read_b128 v[174:177], v144 offset:1024
	ds_read_b128 v[178:181], v144 offset:2048
	ds_read_b128 v[182:185], v144 offset:3072
	ds_read_b128 v[186:189], v157 offset:32768
	ds_read_b128 v[190:193], v157 offset:33792
	ds_read_b128 v[204:207], v157 offset:34816
	ds_read_b128 v[208:211], v157 offset:35840
	ds_read_b128 v[212:215], v157 offset:36864
	ds_read_b128 v[216:219], v157 offset:37888
	ds_read_b128 v[220:223], v157 offset:38912
	ds_read_b128 v[224:227], v157 offset:39936
	s_waitcnt vmcnt(8)
	s_waitcnt lgkmcnt(0)
	s_barrier
	s_setprio 1
	s_waitcnt lgkmcnt(0)
	v_mfma_f32_16x16x32_bf16 v[126:129], v[140:143], v[186:189], v[126:129]
	v_mfma_f32_16x16x32_bf16 v[122:125], v[162:165], v[186:189], v[122:125]
	v_mfma_f32_16x16x32_bf16 v[110:113], v[140:143], v[204:207], v[110:113]
	v_mfma_f32_16x16x32_bf16 v[106:109], v[162:165], v[204:207], v[106:109]
	v_mfma_f32_16x16x32_bf16 v[94:97], v[140:143], v[212:215], v[94:97]
	v_mfma_f32_16x16x32_bf16 v[90:93], v[162:165], v[212:215], v[90:93]
	v_mfma_f32_16x16x32_bf16 v[78:81], v[140:143], v[220:223], v[78:81]
	v_mfma_f32_16x16x32_bf16 v[74:77], v[162:165], v[220:223], v[74:77]
	v_mfma_f32_16x16x32_bf16 v[126:129], v[158:161], v[190:193], v[126:129]
	v_mfma_f32_16x16x32_bf16 v[122:125], v[166:169], v[190:193], v[122:125]
	v_mfma_f32_16x16x32_bf16 v[110:113], v[158:161], v[208:211], v[110:113]
	v_mfma_f32_16x16x32_bf16 v[106:109], v[166:169], v[208:211], v[106:109]
	v_mfma_f32_16x16x32_bf16 v[94:97], v[158:161], v[216:219], v[94:97]
	v_mfma_f32_16x16x32_bf16 v[90:93], v[166:169], v[216:219], v[90:93]
	v_mfma_f32_16x16x32_bf16 v[78:81], v[158:161], v[224:227], v[78:81]
	v_mfma_f32_16x16x32_bf16 v[74:77], v[166:169], v[224:227], v[74:77]
	s_setprio 0
	s_setprio 1
	v_mfma_f32_16x16x32_bf16 v[118:121], v[170:173], v[186:189], v[118:121]
	v_mfma_f32_16x16x32_bf16 v[114:117], v[178:181], v[186:189], v[114:117]
	v_mfma_f32_16x16x32_bf16 v[102:105], v[170:173], v[204:207], v[102:105]
	v_mfma_f32_16x16x32_bf16 v[98:101], v[178:181], v[204:207], v[98:101]
	v_mfma_f32_16x16x32_bf16 v[86:89], v[170:173], v[212:215], v[86:89]
	v_mfma_f32_16x16x32_bf16 v[82:85], v[178:181], v[212:215], v[82:85]
	v_mfma_f32_16x16x32_bf16 v[70:73], v[170:173], v[220:223], v[70:73]
	v_mfma_f32_16x16x32_bf16 v[66:69], v[178:181], v[220:223], v[66:69]
	v_mfma_f32_16x16x32_bf16 v[118:121], v[174:177], v[190:193], v[118:121]
	v_mfma_f32_16x16x32_bf16 v[114:117], v[182:185], v[190:193], v[114:117]
	v_mfma_f32_16x16x32_bf16 v[102:105], v[174:177], v[208:211], v[102:105]
	v_mfma_f32_16x16x32_bf16 v[98:101], v[182:185], v[208:211], v[98:101]
	v_mfma_f32_16x16x32_bf16 v[86:89], v[174:177], v[216:219], v[86:89]
	v_mfma_f32_16x16x32_bf16 v[82:85], v[182:185], v[216:219], v[82:85]
	v_mfma_f32_16x16x32_bf16 v[70:73], v[174:177], v[224:227], v[70:73]
	v_mfma_f32_16x16x32_bf16 v[66:69], v[182:185], v[224:227], v[66:69]
	s_setprio 0
	s_barrier
; #define PG8_STAGE(bufoff, gbase, voff) do { _Pragma("unroll") for (int _i = 0; _i < 2; ++_i) \
;         __builtin_amdgcn_global_load_lds((const unsigned*)((const char*)(gbase) + (voff)[_i]), (PG8_LAS unsigned*)(lds + (bufoff) + ldsw + _i * 8192), 16, 0, 0); } while (0)
; #define PG8_LDA(dst, b, h) do { _Pragma("unroll") for (int m = 0; m < 4; ++m) _Pragma("unroll") for (int k = 0; k < 2; ++k) dst[m][k] = *(const PG8_LAS bf16x8*)(lds + PG8_SA(b, h) + aoff + m * 2048 + k * 1024); } while (0)
; #define PG8_MMA(ai, bj, At, Bt) do { __builtin_amdgcn_s_setprio(1); _Pragma("unroll") for (int m = 0; m < 4; ++m) _Pragma("unroll") for (int n = 0; n < 2; ++n) _Pragma("unroll") for (int k = 0; k < 2; ++k) \
;         acc[ai][bj][m][n] = __builtin_amdgcn_mfma_f32_16x16x32_bf16(Bt[n][k], At[m][k], acc[ai][bj][m][n], 0, 0, 0); __builtin_amdgcn_s_setprio(0); } while (0)
; #define PG8_WAIT_V(n) asm volatile("s_waitcnt vmcnt(" #n ")" ::: "memory")
; #define PG8_WAIT_L(n) asm volatile("s_waitcnt lgkmcnt(" #n ")" ::: "memory")
; #define PG8_BAR __builtin_amdgcn_s_barrier()
; #define PG8_SCHED __builtin_amdgcn_sched_barrier(0)
; template <class Epi, class Sched, bool ALIGN_EPI = false, bool SP2 = false>
; __device__ __forceinline__ void gemm_phase(PG8_LAS unsigned char* lds, const Gemm g, const Sched& S, const Epi& E) {
;     ...
;         for (int t = 0; t < nt; t += 2) {
;     ...
;             PG8_LDA(At, 1, 1); PG8_STAGE(PG8_SB(1, 0), b3, voffB); PG8_STAGE(PG8_SB(1, 1), b3 + hstep, voffB); PG8_STAGE(PG8_SA(1, 0), a3, voffA);
;             PG8_WAIT_V(8); PG8_WAIT_L(0); PG8_BAR; PG8_MMA(1, 0, At, B0); PG8_MMA(1, 1, At, B1); PG8_BAR; PG8_SCHED;
	s_add_i32 s37, s37, s16
	v_lshl_add_u64 v[146:147], v[146:147], 0, s[28:29]
	s_mov_b32 m0, s37
	s_nop 0
	global_load_lds_dwordx4 v[146:147], off
	s_add_i32 m0, s37, 0x2000
	s_add_u32 s20, s20, 0x40080
	v_lshl_add_u64 v[146:147], v[150:151], 0, s[28:29]
	s_addc_u32 s21, s21, 0
	s_add_i32 s37, s56, s16
	global_load_lds_dwordx4 v[146:147], off
	v_lshl_add_u64 v[146:147], s[20:21], 0, v[0:1]
	s_mov_b32 m0, s37
	s_nop 0
	global_load_lds_dwordx4 v[146:147], off
	v_lshl_add_u64 v[146:147], s[20:21], 0, v[130:131]
	s_add_i32 m0, s37, 0x2000
	s_nop 0
	global_load_lds_dwordx4 v[146:147], off
	v_lshl_add_u64 v[146:147], v[154:155], 0, s[28:29]
	s_mov_b32 m0, s35
	s_nop 0
	global_load_lds_dwordx4 v[146:147], off
	v_lshl_add_u64 v[146:147], v[228:229], 0, s[28:29]
	s_mov_b32 m0, s36
	s_nop 0
	global_load_lds_dwordx4 v[146:147], off
	ds_read_b128 v[186:189], v157 offset:49152
	ds_read_b128 v[190:193], v157 offset:50176
	ds_read_b128 v[204:207], v157 offset:51200
	ds_read_b128 v[208:211], v157 offset:52224
	ds_read_b128 v[212:215], v157 offset:53248
	ds_read_b128 v[216:219], v157 offset:54272
	ds_read_b128 v[220:223], v157 offset:55296
	ds_read_b128 v[224:227], v157 offset:56320
	s_waitcnt vmcnt(8)
	s_waitcnt lgkmcnt(0)
	s_barrier
	s_setprio 1
	s_waitcnt lgkmcnt(0)
	v_mfma_f32_16x16x32_bf16 v[62:65], v[140:143], v[186:189], v[62:65]
	v_mfma_f32_16x16x32_bf16 v[58:61], v[162:165], v[186:189], v[58:61]
	v_mfma_f32_16x16x32_bf16 v[46:49], v[140:143], v[204:207], v[46:49]
	v_mfma_f32_16x16x32_bf16 v[42:45], v[162:165], v[204:207], v[42:45]
	v_mfma_f32_16x16x32_bf16 v[30:33], v[140:143], v[212:215], v[30:33]
	v_mfma_f32_16x16x32_bf16 v[26:29], v[162:165], v[212:215], v[26:29]
	v_mfma_f32_16x16x32_bf16 v[14:17], v[140:143], v[220:223], v[14:17]
	v_mfma_f32_16x16x32_bf16 v[10:13], v[162:165], v[220:223], v[10:13]
	v_mfma_f32_16x16x32_bf16 v[62:65], v[158:161], v[190:193], v[62:65]
	v_mfma_f32_16x16x32_bf16 v[58:61], v[166:169], v[190:193], v[58:61]
	v_mfma_f32_16x16x32_bf16 v[46:49], v[158:161], v[208:211], v[46:49]
	v_mfma_f32_16x16x32_bf16 v[42:45], v[166:169], v[208:211], v[42:45]
	v_mfma_f32_16x16x32_bf16 v[30:33], v[158:161], v[216:219], v[30:33]
	v_mfma_f32_16x16x32_bf16 v[26:29], v[166:169], v[216:219], v[26:29]
	v_mfma_f32_16x16x32_bf16 v[14:17], v[158:161], v[224:227], v[14:17]
	v_mfma_f32_16x16x32_bf16 v[10:13], v[166:169], v[224:227], v[10:13]
	s_setprio 0
	s_setprio 1
	v_mfma_f32_16x16x32_bf16 v[54:57], v[170:173], v[186:189], v[54:57]
	v_mfma_f32_16x16x32_bf16 v[50:53], v[178:181], v[186:189], v[50:53]
	v_mfma_f32_16x16x32_bf16 v[38:41], v[170:173], v[204:207], v[38:41]
	v_mfma_f32_16x16x32_bf16 v[34:37], v[178:181], v[204:207], v[34:37]
	v_mfma_f32_16x16x32_bf16 v[22:25], v[170:173], v[212:215], v[22:25]
	v_mfma_f32_16x16x32_bf16 v[18:21], v[178:181], v[212:215], v[18:21]
	v_mfma_f32_16x16x32_bf16 v[6:9], v[170:173], v[220:223], v[6:9]
	v_mfma_f32_16x16x32_bf16 v[2:5], v[178:181], v[220:223], v[2:5]
	v_mfma_f32_16x16x32_bf16 v[54:57], v[174:177], v[190:193], v[54:57]
	v_mfma_f32_16x16x32_bf16 v[50:53], v[182:185], v[190:193], v[50:53]
	v_mfma_f32_16x16x32_bf16 v[38:41], v[174:177], v[208:211], v[38:41]
	v_mfma_f32_16x16x32_bf16 v[34:37], v[182:185], v[208:211], v[34:37]
	v_mfma_f32_16x16x32_bf16 v[22:25], v[174:177], v[216:219], v[22:25]
	v_mfma_f32_16x16x32_bf16 v[18:21], v[182:185], v[216:219], v[18:21]
	v_mfma_f32_16x16x32_bf16 v[6:9], v[174:177], v[224:227], v[6:9]
	v_mfma_f32_16x16x32_bf16 v[2:5], v[182:185], v[224:227], v[2:5]
	s_setprio 0
	s_barrier
	s_add_i32 s55, s55, 2
	s_add_u32 s8, s8, 0x100
	s_addc_u32 s9, s9, 0
	s_add_u32 s53, s53, 0x100
	s_addc_u32 s54, s54, 0
	s_cmp_gt_u32 s55, 13
	s_cbranch_scc0 .LBB0_317
	s_and_b64 vcc, exec, s[6:7]
	s_cbranch_vccz .LBB0_320
	s_barrier

; #define PG8_STAGE(bufoff, gbase, voff) do { _Pragma("unroll") for (int _i = 0; _i < 2; ++_i) \
;         __builtin_amdgcn_global_load_lds((const unsigned*)((const char*)(gbase) + (voff)[_i]), (PG8_LAS unsigned*)(lds + (bufoff) + ldsw + _i * 8192), 16, 0, 0); } while (0)
; #define PG8_LDA(dst, b, h) do { _Pragma("unroll") for (int m = 0; m < 4; ++m) _Pragma("unroll") for (int k = 0; k < 2; ++k) dst[m][k] = *(const PG8_LAS bf16x8*)(lds + PG8_SA(b, h) + aoff + m * 2048 + k * 1024); } while (0)
; #define PG8_LDB(dst, b, h) do { _Pragma("unroll") for (int n = 0; n < 2; ++n) _Pragma("unroll") for (int k = 0; k < 2; ++k) dst[n][k] = *(const PG8_LAS bf16x8*)(lds + PG8_SB(b, h) + boff + n * 2048 + k * 1024); } while (0)
; #define PG8_MMA(ai, bj, At, Bt) do { __builtin_amdgcn_s_setprio(1); _Pragma("unroll") for (int m = 0; m < 4; ++m) _Pragma("unroll") for (int n = 0; n < 2; ++n) _Pragma("unroll") for (int k = 0; k < 2; ++k) \
;         acc[ai][bj][m][n] = __builtin_amdgcn_mfma_f32_16x16x32_bf16(Bt[n][k], At[m][k], acc[ai][bj][m][n], 0, 0, 0); __builtin_amdgcn_s_setprio(0); } while (0)
; #define PG8_WAIT_V(n) asm volatile("s_waitcnt vmcnt(" #n ")" ::: "memory")
; #define PG8_WAIT_L(n) asm volatile("s_waitcnt lgkmcnt(" #n ")" ::: "memory")
; #define PG8_BAR __builtin_amdgcn_s_barrier()
; #define PG8_SCHED __builtin_amdgcn_sched_barrier(0)
; template <class Epi, class Sched, bool ALIGN_EPI = false, bool SP2 = false>
; __device__ __forceinline__ void gemm_phase(PG8_LAS unsigned char* lds, const Gemm g, const Sched& S, const Epi& E) {
;     ...
;             PG8_LDB(B0, 0, 0); PG8_LDB(B1, 0, 1); PG8_SCHED; PG8_LDA(At, 0, 0); PG8_STAGE(PG8_SA(1, 1), a1 + hstep, voffA);
;             PG8_WAIT_V(8); PG8_WAIT_L(0); PG8_BAR; PG8_MMA(0, 0, At, B0); PG8_MMA(0, 1, At, B1); PG8_BAR; PG8_SCHED;
;             PG8_LDA(At, 0, 1); PG8_STAGE(PG8_SB(0, 0), b2, voffB); PG8_STAGE(PG8_SB(0, 1), b2 + hstep, voffB); PG8_STAGE(PG8_SA(0, 0), a2, voffA);
;             PG8_WAIT_V(8); PG8_WAIT_L(0); PG8_BAR; PG8_MMA(1, 0, At, B0); PG8_MMA(1, 1, At, B1); PG8_BAR; PG8_SCHED;
.LBB0_390:
	s_add_u32 s20, s8, 0x100
	s_addc_u32 s21, s9, 0
	s_add_i32 s37, 0, 0x10000
	s_cmp_eq_u32 s57, 40
	s_cselect_b32 s51, s45, s21
	s_cselect_b32 s50, s44, s20
	s_cselect_b32 s49, s47, s56
	s_cselect_b32 s48, s46, s55
	s_add_i32 s58, 0, 0x14000
	v_lshl_add_u64 v[192:193], s[8:9], 0, v[144:145]
	s_add_i32 m0, s18, 0xc000
	s_nop 0
	global_load_lds_dwordx4 v[192:193], off
	v_lshl_add_u64 v[192:193], s[8:9], 0, v[146:147]
	s_add_i32 m0, s18, 0xe000
	s_nop 0
	global_load_lds_dwordx4 v[192:193], off
	v_add_u32_e32 v152, s37, v157
	v_add_u32_e32 v163, s58, v157
	ds_read_b128 v[130:133], v152
	ds_read_b128 v[134:137], v152 offset:1024
	ds_read_b128 v[148:151], v152 offset:2048
	ds_read_b128 v[152:155], v152 offset:3072
	ds_read_b128 v[164:167], v163
	ds_read_b128 v[168:171], v163 offset:1024
	ds_read_b128 v[172:175], v163 offset:2048
	ds_read_b128 v[176:179], v163 offset:3072
	ds_read_b128 v[180:183], v161
	ds_read_b128 v[184:187], v161 offset:1024
	ds_read_b128 v[188:191], v161 offset:2048
	ds_read_b128 v[204:207], v161 offset:3072
	ds_read_b128 v[208:211], v161 offset:4096
	ds_read_b128 v[212:215], v161 offset:5120
	ds_read_b128 v[216:219], v161 offset:6144
	ds_read_b128 v[220:223], v161 offset:7168
	s_waitcnt vmcnt(8)
	s_waitcnt lgkmcnt(0)
	s_barrier
	s_setprio 1
	s_waitcnt lgkmcnt(0)
	v_mfma_f32_16x16x32_bf16 v[126:129], v[130:133], v[180:183], v[126:129]
	v_mfma_f32_16x16x32_bf16 v[122:125], v[148:151], v[180:183], v[122:125]
	v_mfma_f32_16x16x32_bf16 v[110:113], v[130:133], v[188:191], v[110:113]
	v_mfma_f32_16x16x32_bf16 v[106:109], v[148:151], v[188:191], v[106:109]
	v_mfma_f32_16x16x32_bf16 v[94:97], v[130:133], v[208:211], v[94:97]
	v_mfma_f32_16x16x32_bf16 v[90:93], v[148:151], v[208:211], v[90:93]
	v_mfma_f32_16x16x32_bf16 v[78:81], v[130:133], v[216:219], v[78:81]
	v_mfma_f32_16x16x32_bf16 v[74:77], v[148:151], v[216:219], v[74:77]
	v_mfma_f32_16x16x32_bf16 v[126:129], v[134:137], v[184:187], v[126:129]
	v_mfma_f32_16x16x32_bf16 v[122:125], v[152:155], v[184:187], v[122:125]
	v_mfma_f32_16x16x32_bf16 v[110:113], v[134:137], v[204:207], v[110:113]
	v_mfma_f32_16x16x32_bf16 v[106:109], v[152:155], v[204:207], v[106:109]
	v_mfma_f32_16x16x32_bf16 v[94:97], v[134:137], v[212:215], v[94:97]
	v_mfma_f32_16x16x32_bf16 v[90:93], v[152:155], v[212:215], v[90:93]
	v_mfma_f32_16x16x32_bf16 v[78:81], v[134:137], v[220:223], v[78:81]
	v_mfma_f32_16x16x32_bf16 v[74:77], v[152:155], v[220:223], v[74:77]
	s_setprio 0
	s_setprio 1
	v_mfma_f32_16x16x32_bf16 v[118:121], v[164:167], v[180:183], v[118:121]
	v_mfma_f32_16x16x32_bf16 v[114:117], v[172:175], v[180:183], v[114:117]
	v_mfma_f32_16x16x32_bf16 v[102:105], v[164:167], v[188:191], v[102:105]
	v_mfma_f32_16x16x32_bf16 v[98:101], v[172:175], v[188:191], v[98:101]
	v_mfma_f32_16x16x32_bf16 v[86:89], v[164:167], v[208:211], v[86:89]
	v_mfma_f32_16x16x32_bf16 v[82:85], v[172:175], v[208:211], v[82:85]
	v_mfma_f32_16x16x32_bf16 v[70:73], v[164:167], v[216:219], v[70:73]
	v_mfma_f32_16x16x32_bf16 v[66:69], v[172:175], v[216:219], v[66:69]
	v_mfma_f32_16x16x32_bf16 v[118:121], v[168:171], v[184:187], v[118:121]
	v_mfma_f32_16x16x32_bf16 v[114:117], v[176:179], v[184:187], v[114:117]
	v_mfma_f32_16x16x32_bf16 v[102:105], v[168:171], v[204:207], v[102:105]
	v_mfma_f32_16x16x32_bf16 v[98:101], v[176:179], v[204:207], v[98:101]
	v_mfma_f32_16x16x32_bf16 v[86:89], v[168:171], v[212:215], v[86:89]
	v_mfma_f32_16x16x32_bf16 v[82:85], v[176:179], v[212:215], v[82:85]
	v_mfma_f32_16x16x32_bf16 v[70:73], v[168:171], v[220:223], v[70:73]
	v_mfma_f32_16x16x32_bf16 v[66:69], v[176:179], v[220:223], v[66:69]
	s_setprio 0
	s_barrier
	s_add_i32 s8, s37, s16
	v_lshl_add_u64 v[192:193], s[48:49], 0, v[0:1]
	s_mov_b32 m0, s8
	s_nop 0
	global_load_lds_dwordx4 v[192:193], off
	s_add_i32 m0, s8, 0x2000
	s_add_u32 s8, s48, 0xb0000
	v_lshl_add_u64 v[224:225], s[48:49], 0, v[138:139]
	s_addc_u32 s9, s49, 0
	s_add_i32 s37, s58, s16
	global_load_lds_dwordx4 v[224:225], off
	v_lshl_add_u64 v[226:227], s[8:9], 0, v[0:1]
	s_mov_b32 m0, s37
	v_lshl_add_u64 v[228:229], s[50:51], 0, v[140:141]
	global_load_lds_dwordx4 v[226:227], off
	v_lshl_add_u64 v[226:227], s[8:9], 0, v[138:139]
	s_add_i32 m0, s37, 0x2000
	s_nop 0
	global_load_lds_dwordx4 v[226:227], off
	v_lshl_add_u64 v[226:227], s[50:51], 0, v[142:143]
	s_mov_b32 m0, s18
	s_nop 0
	global_load_lds_dwordx4 v[226:227], off
	s_mov_b32 m0, s19
	s_nop 0
	global_load_lds_dwordx4 v[228:229], off
	ds_read_b128 v[180:183], v161 offset:16384
	ds_read_b128 v[184:187], v161 offset:17408
	ds_read_b128 v[188:191], v161 offset:18432
	ds_read_b128 v[204:207], v161 offset:19456
	ds_read_b128 v[208:211], v161 offset:20480
	ds_read_b128 v[212:215], v161 offset:21504
	ds_read_b128 v[216:219], v161 offset:22528
	ds_read_b128 v[220:223], v161 offset:23552
	s_waitcnt vmcnt(8)
	s_waitcnt lgkmcnt(0)
	s_barrier
; #define PG8_STAGE(bufoff, gbase, voff) do { _Pragma("unroll") for (int _i = 0; _i < 2; ++_i) \
;         __builtin_amdgcn_global_load_lds((const unsigned*)((const char*)(gbase) + (voff)[_i]), (PG8_LAS unsigned*)(lds + (bufoff) + ldsw + _i * 8192), 16, 0, 0); } while (0)
; #define PG8_LDA(dst, b, h) do { _Pragma("unroll") for (int m = 0; m < 4; ++m) _Pragma("unroll") for (int k = 0; k < 2; ++k) dst[m][k] = *(const PG8_LAS bf16x8*)(lds + PG8_SA(b, h) + aoff + m * 2048 + k * 1024); } while (0)
; #define PG8_LDB(dst, b, h) do { _Pragma("unroll") for (int n = 0; n < 2; ++n) _Pragma("unroll") for (int k = 0; k < 2; ++k) dst[n][k] = *(const PG8_LAS bf16x8*)(lds + PG8_SB(b, h) + boff + n * 2048 + k * 1024); } while (0)
; #define PG8_MMA(ai, bj, At, Bt) do { __builtin_amdgcn_s_setprio(1); _Pragma("unroll") for (int m = 0; m < 4; ++m) _Pragma("unroll") for (int n = 0; n < 2; ++n) _Pragma("unroll") for (int k = 0; k < 2; ++k) \
;         acc[ai][bj][m][n] = __builtin_amdgcn_mfma_f32_16x16x32_bf16(Bt[n][k], At[m][k], acc[ai][bj][m][n], 0, 0, 0); __builtin_amdgcn_s_setprio(0); } while (0)
; #define PG8_WAIT_V(n) asm volatile("s_waitcnt vmcnt(" #n ")" ::: "memory")
; #define PG8_WAIT_L(n) asm volatile("s_waitcnt lgkmcnt(" #n ")" ::: "memory")
; #define PG8_BAR __builtin_amdgcn_s_barrier()
; #define PG8_SCHED __builtin_amdgcn_sched_barrier(0)
; template <class Epi, class Sched, bool ALIGN_EPI = false, bool SP2 = false>
; __device__ __forceinline__ void gemm_phase(PG8_LAS unsigned char* lds, const Gemm g, const Sched& S, const Epi& E) {
;     ...
;             PG8_WAIT_V(8); PG8_WAIT_L(0); PG8_BAR; PG8_MMA(1, 0, At, B0); PG8_MMA(1, 1, At, B1); PG8_BAR; PG8_SCHED;
;             PG8_LDB(B0, 1, 0); PG8_LDB(B1, 1, 1); PG8_SCHED; PG8_LDA(At, 1, 0); PG8_STAGE(PG8_SA(0, 1), a2 + hstep, voffA);
;             PG8_WAIT_V(8); PG8_WAIT_L(0); PG8_BAR; PG8_MMA(0, 0, At, B0); PG8_MMA(0, 1, At, B1); PG8_BAR; PG8_SCHED;
	s_setprio 1
	s_waitcnt lgkmcnt(0)
	v_mfma_f32_16x16x32_bf16 v[62:65], v[130:133], v[180:183], v[62:65]
	v_mfma_f32_16x16x32_bf16 v[58:61], v[148:151], v[180:183], v[58:61]
	v_mfma_f32_16x16x32_bf16 v[46:49], v[130:133], v[188:191], v[46:49]
	v_mfma_f32_16x16x32_bf16 v[42:45], v[148:151], v[188:191], v[42:45]
	v_mfma_f32_16x16x32_bf16 v[30:33], v[130:133], v[208:211], v[30:33]
	v_mfma_f32_16x16x32_bf16 v[26:29], v[148:151], v[208:211], v[26:29]
	v_mfma_f32_16x16x32_bf16 v[14:17], v[130:133], v[216:219], v[14:17]
	v_mfma_f32_16x16x32_bf16 v[10:13], v[148:151], v[216:219], v[10:13]
	v_mfma_f32_16x16x32_bf16 v[62:65], v[134:137], v[184:187], v[62:65]
	v_mfma_f32_16x16x32_bf16 v[58:61], v[152:155], v[184:187], v[58:61]
	v_mfma_f32_16x16x32_bf16 v[46:49], v[134:137], v[204:207], v[46:49]
	v_mfma_f32_16x16x32_bf16 v[42:45], v[152:155], v[204:207], v[42:45]
	v_mfma_f32_16x16x32_bf16 v[30:33], v[134:137], v[212:215], v[30:33]
	v_mfma_f32_16x16x32_bf16 v[26:29], v[152:155], v[212:215], v[26:29]
	v_mfma_f32_16x16x32_bf16 v[14:17], v[134:137], v[220:223], v[14:17]
	v_mfma_f32_16x16x32_bf16 v[10:13], v[152:155], v[220:223], v[10:13]
	s_setprio 0
	s_setprio 1
	v_mfma_f32_16x16x32_bf16 v[54:57], v[164:167], v[180:183], v[54:57]
	v_mfma_f32_16x16x32_bf16 v[50:53], v[172:175], v[180:183], v[50:53]
	v_mfma_f32_16x16x32_bf16 v[38:41], v[164:167], v[188:191], v[38:41]
	v_mfma_f32_16x16x32_bf16 v[34:37], v[172:175], v[188:191], v[34:37]
	v_mfma_f32_16x16x32_bf16 v[22:25], v[164:167], v[208:211], v[22:25]
	v_mfma_f32_16x16x32_bf16 v[18:21], v[172:175], v[208:211], v[18:21]
	v_mfma_f32_16x16x32_bf16 v[6:9], v[164:167], v[216:219], v[6:9]
	v_mfma_f32_16x16x32_bf16 v[2:5], v[172:175], v[216:219], v[2:5]
	v_mfma_f32_16x16x32_bf16 v[54:57], v[168:171], v[184:187], v[54:57]
	v_mfma_f32_16x16x32_bf16 v[50:53], v[176:179], v[184:187], v[50:53]
	v_mfma_f32_16x16x32_bf16 v[38:41], v[168:171], v[204:207], v[38:41]
	v_mfma_f32_16x16x32_bf16 v[34:37], v[176:179], v[204:207], v[34:37]
	v_mfma_f32_16x16x32_bf16 v[22:25], v[168:171], v[212:215], v[22:25]
	v_mfma_f32_16x16x32_bf16 v[18:21], v[176:179], v[212:215], v[18:21]
	v_mfma_f32_16x16x32_bf16 v[6:9], v[168:171], v[220:223], v[6:9]
	v_mfma_f32_16x16x32_bf16 v[2:5], v[176:179], v[220:223], v[2:5]
	s_setprio 0
	s_barrier
	s_add_i32 s37, 0, 0x18000
	s_add_i32 s58, 0, 0x1c000
	s_add_u32 s8, s50, 0xb0000
	s_addc_u32 s9, s51, 0
	s_mov_b32 m0, s33
	v_lshl_add_u64 v[230:231], s[8:9], 0, v[142:143]
	global_load_lds_dwordx4 v[230:231], off
	v_lshl_add_u64 v[230:231], s[8:9], 0, v[140:141]
	s_mov_b32 m0, s34
	s_nop 0
	global_load_lds_dwordx4 v[230:231], off
	v_add_u32_e32 v152, s37, v157
	v_add_u32_e32 v163, s58, v157
	ds_read_b128 v[130:133], v152
	ds_read_b128 v[134:137], v152 offset:1024
	ds_read_b128 v[148:151], v152 offset:2048
	ds_read_b128 v[152:155], v152 offset:3072
	ds_read_b128 v[164:167], v163
	ds_read_b128 v[168:171], v163 offset:1024
	ds_read_b128 v[172:175], v163 offset:2048
	ds_read_b128 v[176:179], v163 offset:3072
	ds_read_b128 v[180:183], v161 offset:32768
	ds_read_b128 v[184:187], v161 offset:33792
	ds_read_b128 v[188:191], v161 offset:34816
	ds_read_b128 v[204:207], v161 offset:35840
	ds_read_b128 v[208:211], v161 offset:36864
	ds_read_b128 v[212:215], v161 offset:37888
	ds_read_b128 v[216:219], v161 offset:38912
	ds_read_b128 v[220:223], v161 offset:39936
	s_waitcnt vmcnt(8)
	s_waitcnt lgkmcnt(0)
	s_barrier
	s_setprio 1
	s_waitcnt lgkmcnt(0)
	v_mfma_f32_16x16x32_bf16 v[126:129], v[130:133], v[180:183], v[126:129]
	v_mfma_f32_16x16x32_bf16 v[122:125], v[148:151], v[180:183], v[122:125]
	v_mfma_f32_16x16x32_bf16 v[110:113], v[130:133], v[188:191], v[110:113]
	v_mfma_f32_16x16x32_bf16 v[106:109], v[148:151], v[188:191], v[106:109]
	v_mfma_f32_16x16x32_bf16 v[94:97], v[130:133], v[208:211], v[94:97]
	v_mfma_f32_16x16x32_bf16 v[90:93], v[148:151], v[208:211], v[90:93]
	v_mfma_f32_16x16x32_bf16 v[78:81], v[130:133], v[216:219], v[78:81]
	v_mfma_f32_16x16x32_bf16 v[74:77], v[148:151], v[216:219], v[74:77]
	v_mfma_f32_16x16x32_bf16 v[126:129], v[134:137], v[184:187], v[126:129]
	v_mfma_f32_16x16x32_bf16 v[122:125], v[152:155], v[184:187], v[122:125]
	v_mfma_f32_16x16x32_bf16 v[110:113], v[134:137], v[204:207], v[110:113]
	v_mfma_f32_16x16x32_bf16 v[106:109], v[152:155], v[204:207], v[106:109]
	v_mfma_f32_16x16x32_bf16 v[94:97], v[134:137], v[212:215], v[94:97]
	v_mfma_f32_16x16x32_bf16 v[90:93], v[152:155], v[212:215], v[90:93]
	v_mfma_f32_16x16x32_bf16 v[78:81], v[134:137], v[220:223], v[78:81]
	v_mfma_f32_16x16x32_bf16 v[74:77], v[152:155], v[220:223], v[74:77]
	s_setprio 0
	s_setprio 1
	v_mfma_f32_16x16x32_bf16 v[118:121], v[164:167], v[180:183], v[118:121]
	v_mfma_f32_16x16x32_bf16 v[114:117], v[172:175], v[180:183], v[114:117]
	v_mfma_f32_16x16x32_bf16 v[102:105], v[164:167], v[188:191], v[102:105]
	v_mfma_f32_16x16x32_bf16 v[98:101], v[172:175], v[188:191], v[98:101]
	v_mfma_f32_16x16x32_bf16 v[86:89], v[164:167], v[208:211], v[86:89]
	v_mfma_f32_16x16x32_bf16 v[82:85], v[172:175], v[208:211], v[82:85]
	v_mfma_f32_16x16x32_bf16 v[70:73], v[164:167], v[216:219], v[70:73]
	v_mfma_f32_16x16x32_bf16 v[66:69], v[172:175], v[216:219], v[66:69]
	v_mfma_f32_16x16x32_bf16 v[118:121], v[168:171], v[184:187], v[118:121]
	v_mfma_f32_16x16x32_bf16 v[114:117], v[176:179], v[184:187], v[114:117]
	v_mfma_f32_16x16x32_bf16 v[102:105], v[168:171], v[204:207], v[102:105]
	v_mfma_f32_16x16x32_bf16 v[98:101], v[176:179], v[204:207], v[98:101]
	v_mfma_f32_16x16x32_bf16 v[86:89], v[168:171], v[212:215], v[86:89]
	v_mfma_f32_16x16x32_bf16 v[82:85], v[176:179], v[212:215], v[82:85]
	v_mfma_f32_16x16x32_bf16 v[70:73], v[168:171], v[220:223], v[70:73]
	v_mfma_f32_16x16x32_bf16 v[66:69], v[176:179], v[220:223], v[66:69]
	s_setprio 0
	s_barrier
; #define PG8_STAGE(bufoff, gbase, voff) do { _Pragma("unroll") for (int _i = 0; _i < 2; ++_i) \
;         __builtin_amdgcn_global_load_lds((const unsigned*)((const char*)(gbase) + (voff)[_i]), (PG8_LAS unsigned*)(lds + (bufoff) + ldsw + _i * 8192), 16, 0, 0); } while (0)
; #define PG8_LDA(dst, b, h) do { _Pragma("unroll") for (int m = 0; m < 4; ++m) _Pragma("unroll") for (int k = 0; k < 2; ++k) dst[m][k] = *(const PG8_LAS bf16x8*)(lds + PG8_SA(b, h) + aoff + m * 2048 + k * 1024); } while (0)
; #define PG8_MMA(ai, bj, At, Bt) do { __builtin_amdgcn_s_setprio(1); _Pragma("unroll") for (int m = 0; m < 4; ++m) _Pragma("unroll") for (int n = 0; n < 2; ++n) _Pragma("unroll") for (int k = 0; k < 2; ++k) \
;         acc[ai][bj][m][n] = __builtin_amdgcn_mfma_f32_16x16x32_bf16(Bt[n][k], At[m][k], acc[ai][bj][m][n], 0, 0, 0); __builtin_amdgcn_s_setprio(0); } while (0)
; #define PG8_WAIT_V(n) asm volatile("s_waitcnt vmcnt(" #n ")" ::: "memory")
; #define PG8_WAIT_L(n) asm volatile("s_waitcnt lgkmcnt(" #n ")" ::: "memory")
; #define PG8_BAR __builtin_amdgcn_s_barrier()
; #define PG8_SCHED __builtin_amdgcn_sched_barrier(0)
; template <class Epi, class Sched, bool ALIGN_EPI = false, bool SP2 = false>
; __device__ __forceinline__ void gemm_phase(PG8_LAS unsigned char* lds, const Gemm g, const Sched& S, const Epi& E) {
;     ...
;         for (int t = 0; t < nt; t += 2) {
;     ...
;             PG8_LDA(At, 1, 1); PG8_STAGE(PG8_SB(1, 0), b3, voffB); PG8_STAGE(PG8_SB(1, 1), b3 + hstep, voffB); PG8_STAGE(PG8_SA(1, 0), a3, voffA);
;             PG8_WAIT_V(8); PG8_WAIT_L(0); PG8_BAR; PG8_MMA(1, 0, At, B0); PG8_MMA(1, 1, At, B1); PG8_BAR; PG8_SCHED;
	s_add_i32 s8, s37, s16
	v_lshl_add_u64 v[192:193], v[192:193], 0, s[28:29]
	s_mov_b32 m0, s8
	s_nop 0
	global_load_lds_dwordx4 v[192:193], off
	s_add_i32 m0, s8, 0x2000
	s_add_u32 s8, s48, 0xb0080
	v_lshl_add_u64 v[192:193], v[224:225], 0, s[28:29]
	s_addc_u32 s9, s49, 0
	s_add_i32 s37, s58, s16
	global_load_lds_dwordx4 v[192:193], off
	v_lshl_add_u64 v[192:193], s[8:9], 0, v[0:1]
	s_mov_b32 m0, s37
	s_nop 0
	global_load_lds_dwordx4 v[192:193], off
	v_lshl_add_u64 v[192:193], s[8:9], 0, v[138:139]
	s_add_i32 m0, s37, 0x2000
	s_nop 0
	global_load_lds_dwordx4 v[192:193], off
	v_lshl_add_u64 v[192:193], v[226:227], 0, s[28:29]
	s_mov_b32 m0, s35
	s_nop 0
	global_load_lds_dwordx4 v[192:193], off
	v_lshl_add_u64 v[192:193], v[228:229], 0, s[28:29]
	s_mov_b32 m0, s36
	s_nop 0
	global_load_lds_dwordx4 v[192:193], off
	ds_read_b128 v[180:183], v161 offset:49152
	ds_read_b128 v[184:187], v161 offset:50176
	ds_read_b128 v[188:191], v161 offset:51200
	ds_read_b128 v[204:207], v161 offset:52224
	ds_read_b128 v[208:211], v161 offset:53248
	ds_read_b128 v[212:215], v161 offset:54272
	ds_read_b128 v[216:219], v161 offset:55296
	ds_read_b128 v[220:223], v161 offset:56320
	s_waitcnt vmcnt(8)
	s_waitcnt lgkmcnt(0)
	s_barrier
	s_setprio 1
	s_waitcnt lgkmcnt(0)
	v_mfma_f32_16x16x32_bf16 v[62:65], v[130:133], v[180:183], v[62:65]
	v_mfma_f32_16x16x32_bf16 v[58:61], v[148:151], v[180:183], v[58:61]
	v_mfma_f32_16x16x32_bf16 v[46:49], v[130:133], v[188:191], v[46:49]
	v_mfma_f32_16x16x32_bf16 v[42:45], v[148:151], v[188:191], v[42:45]
	v_mfma_f32_16x16x32_bf16 v[30:33], v[130:133], v[208:211], v[30:33]
	v_mfma_f32_16x16x32_bf16 v[26:29], v[148:151], v[208:211], v[26:29]
	v_mfma_f32_16x16x32_bf16 v[14:17], v[130:133], v[216:219], v[14:17]
	v_mfma_f32_16x16x32_bf16 v[10:13], v[148:151], v[216:219], v[10:13]
	v_mfma_f32_16x16x32_bf16 v[62:65], v[134:137], v[184:187], v[62:65]
	v_mfma_f32_16x16x32_bf16 v[58:61], v[152:155], v[184:187], v[58:61]
	v_mfma_f32_16x16x32_bf16 v[46:49], v[134:137], v[204:207], v[46:49]
	v_mfma_f32_16x16x32_bf16 v[42:45], v[152:155], v[204:207], v[42:45]
	v_mfma_f32_16x16x32_bf16 v[30:33], v[134:137], v[212:215], v[30:33]
	v_mfma_f32_16x16x32_bf16 v[26:29], v[152:155], v[212:215], v[26:29]
	v_mfma_f32_16x16x32_bf16 v[14:17], v[134:137], v[220:223], v[14:17]
	v_mfma_f32_16x16x32_bf16 v[10:13], v[152:155], v[220:223], v[10:13]
	s_setprio 0
	s_setprio 1
	v_mfma_f32_16x16x32_bf16 v[54:57], v[164:167], v[180:183], v[54:57]
	v_mfma_f32_16x16x32_bf16 v[50:53], v[172:175], v[180:183], v[50:53]
	v_mfma_f32_16x16x32_bf16 v[38:41], v[164:167], v[188:191], v[38:41]
	v_mfma_f32_16x16x32_bf16 v[34:37], v[172:175], v[188:191], v[34:37]
	v_mfma_f32_16x16x32_bf16 v[22:25], v[164:167], v[208:211], v[22:25]
	v_mfma_f32_16x16x32_bf16 v[18:21], v[172:175], v[208:211], v[18:21]
	v_mfma_f32_16x16x32_bf16 v[6:9], v[164:167], v[216:219], v[6:9]
	v_mfma_f32_16x16x32_bf16 v[2:5], v[172:175], v[216:219], v[2:5]
	v_mfma_f32_16x16x32_bf16 v[54:57], v[168:171], v[184:187], v[54:57]
	v_mfma_f32_16x16x32_bf16 v[50:53], v[176:179], v[184:187], v[50:53]
	v_mfma_f32_16x16x32_bf16 v[38:41], v[168:171], v[204:207], v[38:41]
	v_mfma_f32_16x16x32_bf16 v[34:37], v[176:179], v[204:207], v[34:37]
	v_mfma_f32_16x16x32_bf16 v[22:25], v[168:171], v[212:215], v[22:25]
	v_mfma_f32_16x16x32_bf16 v[18:21], v[176:179], v[212:215], v[18:21]
	v_mfma_f32_16x16x32_bf16 v[6:9], v[168:171], v[220:223], v[6:9]
	v_mfma_f32_16x16x32_bf16 v[2:5], v[176:179], v[220:223], v[2:5]
	s_setprio 0
	s_barrier
	s_add_i32 s57, s57, 2
	s_add_u32 s55, s55, 0x100
	s_addc_u32 s56, s56, 0
	s_cmp_gt_u32 s57, 41
	s_mov_b64 s[8:9], s[20:21]
	s_cbranch_scc0 .LBB0_390
	s_and_b64 vcc, exec, s[6:7]
	s_cbranch_vccz .LBB0_393
	s_barrier

; #define PG8_STAGE(bufoff, gbase, voff) do { _Pragma("unroll") for (int _i = 0; _i < 2; ++_i) \
;         __builtin_amdgcn_global_load_lds((const unsigned*)((const char*)(gbase) + (voff)[_i]), (PG8_LAS unsigned*)(lds + (bufoff) + ldsw + _i * 8192), 16, 0, 0); } while (0)
; #define PG8_LDA(dst, b, h) do { _Pragma("unroll") for (int m = 0; m < 4; ++m) _Pragma("unroll") for (int k = 0; k < 2; ++k) dst[m][k] = *(const PG8_LAS bf16x8*)(lds + PG8_SA(b, h) + aoff + m * 2048 + k * 1024); } while (0)
; #define PG8_LDB(dst, b, h) do { _Pragma("unroll") for (int n = 0; n < 2; ++n) _Pragma("unroll") for (int k = 0; k < 2; ++k) dst[n][k] = *(const PG8_LAS bf16x8*)(lds + PG8_SB(b, h) + boff + n * 2048 + k * 1024); } while (0)
; #define PG8_MMA(ai, bj, At, Bt) do { __builtin_amdgcn_s_setprio(1); _Pragma("unroll") for (int m = 0; m < 4; ++m) _Pragma("unroll") for (int n = 0; n < 2; ++n) _Pragma("unroll") for (int k = 0; k < 2; ++k) \
;         acc[ai][bj][m][n] = __builtin_amdgcn_mfma_f32_16x16x32_bf16(Bt[n][k], At[m][k], acc[ai][bj][m][n], 0, 0, 0); __builtin_amdgcn_s_setprio(0); } while (0)
; #define PG8_WAIT_V(n) asm volatile("s_waitcnt vmcnt(" #n ")" ::: "memory")
; #define PG8_WAIT_L(n) asm volatile("s_waitcnt lgkmcnt(" #n ")" ::: "memory")
; #define PG8_BAR __builtin_amdgcn_s_barrier()
; #define PG8_SCHED __builtin_amdgcn_sched_barrier(0)
; template <class Epi, class Sched, bool ALIGN_EPI = false, bool SP2 = false>
; __device__ __forceinline__ void gemm_phase(PG8_LAS unsigned char* lds, const Gemm g, const Sched& S, const Epi& E) {
;     ...
;             PG8_LDB(B0, 0, 0); PG8_LDB(B1, 0, 1); PG8_SCHED; PG8_LDA(At, 0, 0); PG8_STAGE(PG8_SA(1, 1), a1 + hstep, voffA);
;             PG8_WAIT_V(8); PG8_WAIT_L(0); PG8_BAR; PG8_MMA(0, 0, At, B0); PG8_MMA(0, 1, At, B1); PG8_BAR; PG8_SCHED;
;             PG8_LDA(At, 0, 1); PG8_STAGE(PG8_SB(0, 0), b2, voffB); PG8_STAGE(PG8_SB(0, 1), b2 + hstep, voffB); PG8_STAGE(PG8_SA(0, 0), a2, voffA);
;             PG8_WAIT_V(8); PG8_WAIT_L(0); PG8_BAR; PG8_MMA(1, 0, At, B0); PG8_MMA(1, 1, At, B1); PG8_BAR; PG8_SCHED;
.LBB0_478:
	s_add_u32 s37, s20, 0xfffc0080
	s_addc_u32 s40, s21, -1
	s_add_i32 s51, 0, 0x10000
	s_cmp_eq_u32 s50, 12
	s_cselect_b32 s43, s9, s40
	s_cselect_b32 s42, s44, s37
	s_cselect_b32 s41, s7, s49
	s_cselect_b32 s40, s45, s48
	s_add_i32 s37, 0, 0x14000
	v_lshl_add_u64 v[220:221], s[20:21], 0, v[216:217]
	s_add_i32 m0, s3, 0xc000
	s_nop 0
	global_load_lds_dwordx4 v[220:221], off
	v_lshl_add_u64 v[220:221], s[20:21], 0, v[218:219]
	s_add_i32 m0, s3, 0xe000
	s_nop 0
	global_load_lds_dwordx4 v[220:221], off
	v_add_u32_e32 v0, s51, v248
	ds_read_b128 v[74:77], v0
	ds_read_b128 v[86:89], v0 offset:1024
	ds_read_b128 v[98:101], v0 offset:2048
	ds_read_b128 v[102:105], v0 offset:3072
	v_add_u32_e32 v0, s37, v248
	ds_read_b128 v[114:117], v0
	ds_read_b128 v[118:121], v0 offset:1024
	ds_read_b128 v[130:133], v0 offset:2048
	ds_read_b128 v[134:137], v0 offset:3072
	ds_read_b128 v[142:145], v250
	ds_read_b128 v[150:153], v250 offset:1024
	ds_read_b128 v[158:161], v250 offset:2048
	ds_read_b128 v[166:169], v250 offset:3072
	ds_read_b128 v[178:181], v250 offset:4096
	ds_read_b128 v[182:185], v250 offset:5120
	ds_read_b128 v[186:189], v250 offset:6144
	ds_read_b128 v[190:193], v250 offset:7168
	s_waitcnt vmcnt(8)
	s_waitcnt lgkmcnt(0)
	s_barrier
	s_setprio 1
	s_waitcnt lgkmcnt(0)
	v_mfma_f32_16x16x32_bf16 v[174:177], v[74:77], v[142:145], v[174:177]
	v_mfma_f32_16x16x32_bf16 v[170:173], v[98:101], v[142:145], v[170:173]
	v_mfma_f32_16x16x32_bf16 v[146:149], v[74:77], v[158:161], v[146:149]
	v_mfma_f32_16x16x32_bf16 v[138:141], v[98:101], v[158:161], v[138:141]
	v_mfma_f32_16x16x32_bf16 v[110:113], v[74:77], v[178:181], v[110:113]
	v_mfma_f32_16x16x32_bf16 v[106:109], v[98:101], v[178:181], v[106:109]
	v_mfma_f32_16x16x32_bf16 v[82:85], v[74:77], v[186:189], v[82:85]
	v_mfma_f32_16x16x32_bf16 v[78:81], v[98:101], v[186:189], v[78:81]
	v_mfma_f32_16x16x32_bf16 v[174:177], v[86:89], v[150:153], v[174:177]
	v_mfma_f32_16x16x32_bf16 v[170:173], v[102:105], v[150:153], v[170:173]
	v_mfma_f32_16x16x32_bf16 v[146:149], v[86:89], v[166:169], v[146:149]
	v_mfma_f32_16x16x32_bf16 v[138:141], v[102:105], v[166:169], v[138:141]
	v_mfma_f32_16x16x32_bf16 v[110:113], v[86:89], v[182:185], v[110:113]
	v_mfma_f32_16x16x32_bf16 v[106:109], v[102:105], v[182:185], v[106:109]
	v_mfma_f32_16x16x32_bf16 v[82:85], v[86:89], v[190:193], v[82:85]
	v_mfma_f32_16x16x32_bf16 v[78:81], v[102:105], v[190:193], v[78:81]
	s_setprio 0
	s_setprio 1
	v_mfma_f32_16x16x32_bf16 v[162:165], v[114:117], v[142:145], v[162:165]
	v_mfma_f32_16x16x32_bf16 v[126:129], v[114:117], v[158:161], v[126:129]
	v_mfma_f32_16x16x32_bf16 v[122:125], v[130:133], v[158:161], v[122:125]
	v_mfma_f32_16x16x32_bf16 v[94:97], v[114:117], v[178:181], v[94:97]
	v_mfma_f32_16x16x32_bf16 v[90:93], v[130:133], v[178:181], v[90:93]
	v_mfma_f32_16x16x32_bf16 v[70:73], v[114:117], v[186:189], v[70:73]
	v_mfma_f32_16x16x32_bf16 v[66:69], v[130:133], v[186:189], v[66:69]
	v_mfma_f32_16x16x32_bf16 v[162:165], v[118:121], v[150:153], v[162:165]
	v_mfma_f32_16x16x32_bf16 v[142:145], v[130:133], v[142:145], v[154:157]
	v_mfma_f32_16x16x32_bf16 v[126:129], v[118:121], v[166:169], v[126:129]
	v_mfma_f32_16x16x32_bf16 v[122:125], v[134:137], v[166:169], v[122:125]
	v_mfma_f32_16x16x32_bf16 v[94:97], v[118:121], v[182:185], v[94:97]
	v_mfma_f32_16x16x32_bf16 v[90:93], v[134:137], v[182:185], v[90:93]
	v_mfma_f32_16x16x32_bf16 v[70:73], v[118:121], v[190:193], v[70:73]
	v_mfma_f32_16x16x32_bf16 v[66:69], v[134:137], v[190:193], v[66:69]
	v_mfma_f32_16x16x32_bf16 v[142:145], v[134:137], v[150:153], v[142:145]
	s_setprio 0
	s_barrier
	s_add_i32 s51, s51, s2
	v_lshl_add_u64 v[220:221], s[40:41], 0, v[208:209]
	s_mov_b32 m0, s51
	s_nop 0
	global_load_lds_dwordx4 v[220:221], off
	s_add_i32 m0, s51, 0x2000
	s_add_u32 s54, s40, 0x40000
	v_lshl_add_u64 v[222:223], s[40:41], 0, v[204:205]
	s_addc_u32 s55, s41, 0
	s_add_i32 s37, s37, s2
	global_load_lds_dwordx4 v[222:223], off
	v_lshl_add_u64 v[224:225], s[54:55], 0, v[208:209]
	s_mov_b32 m0, s37
	v_lshl_add_u64 v[226:227], s[42:43], 0, v[206:207]
	global_load_lds_dwordx4 v[224:225], off
	v_lshl_add_u64 v[224:225], s[54:55], 0, v[204:205]
	s_add_i32 m0, s37, 0x2000
	s_nop 0
	global_load_lds_dwordx4 v[224:225], off
	v_lshl_add_u64 v[224:225], s[42:43], 0, v[210:211]
	s_mov_b32 m0, s3
	s_nop 0
	global_load_lds_dwordx4 v[224:225], off
	s_mov_b32 m0, s18
	s_nop 0
	global_load_lds_dwordx4 v[226:227], off
	ds_read_b128 v[150:153], v250 offset:16384
	ds_read_b128 v[154:157], v250 offset:17408
	ds_read_b128 v[158:161], v250 offset:18432
	ds_read_b128 v[166:169], v250 offset:19456
	ds_read_b128 v[178:181], v250 offset:20480
	ds_read_b128 v[182:185], v250 offset:21504
	ds_read_b128 v[186:189], v250 offset:22528
	ds_read_b128 v[190:193], v250 offset:23552
	s_waitcnt vmcnt(8)
	s_waitcnt lgkmcnt(0)
	s_barrier
; #define PG8_STAGE(bufoff, gbase, voff) do { _Pragma("unroll") for (int _i = 0; _i < 2; ++_i) \
;         __builtin_amdgcn_global_load_lds((const unsigned*)((const char*)(gbase) + (voff)[_i]), (PG8_LAS unsigned*)(lds + (bufoff) + ldsw + _i * 8192), 16, 0, 0); } while (0)
; #define PG8_LDA(dst, b, h) do { _Pragma("unroll") for (int m = 0; m < 4; ++m) _Pragma("unroll") for (int k = 0; k < 2; ++k) dst[m][k] = *(const PG8_LAS bf16x8*)(lds + PG8_SA(b, h) + aoff + m * 2048 + k * 1024); } while (0)
; #define PG8_LDB(dst, b, h) do { _Pragma("unroll") for (int n = 0; n < 2; ++n) _Pragma("unroll") for (int k = 0; k < 2; ++k) dst[n][k] = *(const PG8_LAS bf16x8*)(lds + PG8_SB(b, h) + boff + n * 2048 + k * 1024); } while (0)
; #define PG8_MMA(ai, bj, At, Bt) do { __builtin_amdgcn_s_setprio(1); _Pragma("unroll") for (int m = 0; m < 4; ++m) _Pragma("unroll") for (int n = 0; n < 2; ++n) _Pragma("unroll") for (int k = 0; k < 2; ++k) \
;         acc[ai][bj][m][n] = __builtin_amdgcn_mfma_f32_16x16x32_bf16(Bt[n][k], At[m][k], acc[ai][bj][m][n], 0, 0, 0); __builtin_amdgcn_s_setprio(0); } while (0)
; #define PG8_WAIT_V(n) asm volatile("s_waitcnt vmcnt(" #n ")" ::: "memory")
; #define PG8_WAIT_L(n) asm volatile("s_waitcnt lgkmcnt(" #n ")" ::: "memory")
; #define PG8_BAR __builtin_amdgcn_s_barrier()
; #define PG8_SCHED __builtin_amdgcn_sched_barrier(0)
; template <class Epi, class Sched, bool ALIGN_EPI = false, bool SP2 = false>
; __device__ __forceinline__ void gemm_phase(PG8_LAS unsigned char* lds, const Gemm g, const Sched& S, const Epi& E) {
;     ...
;             PG8_WAIT_V(8); PG8_WAIT_L(0); PG8_BAR; PG8_MMA(1, 0, At, B0); PG8_MMA(1, 1, At, B1); PG8_BAR; PG8_SCHED;
;             PG8_LDB(B0, 1, 0); PG8_LDB(B1, 1, 1); PG8_SCHED; PG8_LDA(At, 1, 0); PG8_STAGE(PG8_SA(0, 1), a2 + hstep, voffA);
;             PG8_WAIT_V(8); PG8_WAIT_L(0); PG8_BAR; PG8_MMA(0, 0, At, B0); PG8_MMA(0, 1, At, B1); PG8_BAR; PG8_SCHED;
	s_setprio 1
	s_waitcnt lgkmcnt(0)
	v_mfma_f32_16x16x32_bf16 v[62:65], v[74:77], v[150:153], v[62:65]
	v_mfma_f32_16x16x32_bf16 v[58:61], v[98:101], v[150:153], v[58:61]
	v_mfma_f32_16x16x32_bf16 v[46:49], v[74:77], v[158:161], v[46:49]
	v_mfma_f32_16x16x32_bf16 v[42:45], v[98:101], v[158:161], v[42:45]
	v_mfma_f32_16x16x32_bf16 v[30:33], v[74:77], v[178:181], v[30:33]
	v_mfma_f32_16x16x32_bf16 v[26:29], v[98:101], v[178:181], v[26:29]
	v_mfma_f32_16x16x32_bf16 v[14:17], v[74:77], v[186:189], v[14:17]
	v_mfma_f32_16x16x32_bf16 v[10:13], v[98:101], v[186:189], v[10:13]
	v_mfma_f32_16x16x32_bf16 v[62:65], v[86:89], v[154:157], v[62:65]
	v_mfma_f32_16x16x32_bf16 v[58:61], v[102:105], v[154:157], v[58:61]
	v_mfma_f32_16x16x32_bf16 v[46:49], v[86:89], v[166:169], v[46:49]
	v_mfma_f32_16x16x32_bf16 v[42:45], v[102:105], v[166:169], v[42:45]
	v_mfma_f32_16x16x32_bf16 v[30:33], v[86:89], v[182:185], v[30:33]
	v_mfma_f32_16x16x32_bf16 v[26:29], v[102:105], v[182:185], v[26:29]
	v_mfma_f32_16x16x32_bf16 v[14:17], v[86:89], v[190:193], v[14:17]
	v_mfma_f32_16x16x32_bf16 v[10:13], v[102:105], v[190:193], v[10:13]
	s_setprio 0
	s_setprio 1
	v_mfma_f32_16x16x32_bf16 v[54:57], v[114:117], v[150:153], v[54:57]
	v_mfma_f32_16x16x32_bf16 v[50:53], v[130:133], v[150:153], v[50:53]
	v_mfma_f32_16x16x32_bf16 v[38:41], v[114:117], v[158:161], v[38:41]
	v_mfma_f32_16x16x32_bf16 v[34:37], v[130:133], v[158:161], v[34:37]
	v_mfma_f32_16x16x32_bf16 v[22:25], v[114:117], v[178:181], v[22:25]
	v_mfma_f32_16x16x32_bf16 v[18:21], v[130:133], v[178:181], v[18:21]
	v_mfma_f32_16x16x32_bf16 v[6:9], v[114:117], v[186:189], v[6:9]
	v_mfma_f32_16x16x32_bf16 v[2:5], v[130:133], v[186:189], v[2:5]
	v_mfma_f32_16x16x32_bf16 v[54:57], v[118:121], v[154:157], v[54:57]
	v_mfma_f32_16x16x32_bf16 v[50:53], v[134:137], v[154:157], v[50:53]
	v_mfma_f32_16x16x32_bf16 v[38:41], v[118:121], v[166:169], v[38:41]
	v_mfma_f32_16x16x32_bf16 v[34:37], v[134:137], v[166:169], v[34:37]
	v_mfma_f32_16x16x32_bf16 v[22:25], v[118:121], v[182:185], v[22:25]
	v_mfma_f32_16x16x32_bf16 v[18:21], v[134:137], v[182:185], v[18:21]
	v_mfma_f32_16x16x32_bf16 v[6:9], v[118:121], v[190:193], v[6:9]
	v_mfma_f32_16x16x32_bf16 v[2:5], v[134:137], v[190:193], v[2:5]
	s_setprio 0
	s_barrier
	s_add_i32 s37, 0, 0x18000
	s_add_i32 s51, 0, 0x1c000
	s_add_u32 s42, s42, 0x40000
	s_addc_u32 s43, s43, 0
	s_mov_b32 m0, s19
	v_lshl_add_u64 v[228:229], s[42:43], 0, v[210:211]
	global_load_lds_dwordx4 v[228:229], off
	v_lshl_add_u64 v[228:229], s[42:43], 0, v[206:207]
	s_mov_b32 m0, s33
	s_nop 0
	global_load_lds_dwordx4 v[228:229], off
	v_add_u32_e32 v0, s37, v248
	ds_read_b128 v[74:77], v0
	ds_read_b128 v[86:89], v0 offset:1024
	ds_read_b128 v[98:101], v0 offset:2048
	ds_read_b128 v[102:105], v0 offset:3072
	v_add_u32_e32 v0, s51, v248
	ds_read_b128 v[114:117], v0
	ds_read_b128 v[118:121], v0 offset:1024
	ds_read_b128 v[130:133], v0 offset:2048
	ds_read_b128 v[134:137], v0 offset:3072
	ds_read_b128 v[150:153], v250 offset:32768
	ds_read_b128 v[154:157], v250 offset:33792
	ds_read_b128 v[158:161], v250 offset:34816
	ds_read_b128 v[166:169], v250 offset:35840
	ds_read_b128 v[178:181], v250 offset:36864
	ds_read_b128 v[182:185], v250 offset:37888
	ds_read_b128 v[186:189], v250 offset:38912
	ds_read_b128 v[190:193], v250 offset:39936
	s_waitcnt vmcnt(8)
	s_waitcnt lgkmcnt(0)
	s_barrier
	s_setprio 1
	s_waitcnt lgkmcnt(0)
	v_mfma_f32_16x16x32_bf16 v[174:177], v[74:77], v[150:153], v[174:177]
	v_mfma_f32_16x16x32_bf16 v[170:173], v[98:101], v[150:153], v[170:173]
	v_mfma_f32_16x16x32_bf16 v[146:149], v[74:77], v[158:161], v[146:149]
	v_mfma_f32_16x16x32_bf16 v[138:141], v[98:101], v[158:161], v[138:141]
	v_mfma_f32_16x16x32_bf16 v[110:113], v[74:77], v[178:181], v[110:113]
	v_mfma_f32_16x16x32_bf16 v[106:109], v[98:101], v[178:181], v[106:109]
	v_mfma_f32_16x16x32_bf16 v[82:85], v[74:77], v[186:189], v[82:85]
	v_mfma_f32_16x16x32_bf16 v[78:81], v[98:101], v[186:189], v[78:81]
	v_mfma_f32_16x16x32_bf16 v[174:177], v[86:89], v[154:157], v[174:177]
	v_mfma_f32_16x16x32_bf16 v[170:173], v[102:105], v[154:157], v[170:173]
	v_mfma_f32_16x16x32_bf16 v[146:149], v[86:89], v[166:169], v[146:149]
	v_mfma_f32_16x16x32_bf16 v[138:141], v[102:105], v[166:169], v[138:141]
	v_mfma_f32_16x16x32_bf16 v[110:113], v[86:89], v[182:185], v[110:113]
	v_mfma_f32_16x16x32_bf16 v[106:109], v[102:105], v[182:185], v[106:109]
	v_mfma_f32_16x16x32_bf16 v[82:85], v[86:89], v[190:193], v[82:85]
	v_mfma_f32_16x16x32_bf16 v[78:81], v[102:105], v[190:193], v[78:81]
	s_setprio 0
	s_setprio 1
	v_mfma_f32_16x16x32_bf16 v[162:165], v[114:117], v[150:153], v[162:165]
	v_mfma_f32_16x16x32_bf16 v[142:145], v[130:133], v[150:153], v[142:145]
	v_mfma_f32_16x16x32_bf16 v[126:129], v[114:117], v[158:161], v[126:129]
	v_mfma_f32_16x16x32_bf16 v[122:125], v[130:133], v[158:161], v[122:125]
	v_mfma_f32_16x16x32_bf16 v[94:97], v[114:117], v[178:181], v[94:97]
	v_mfma_f32_16x16x32_bf16 v[90:93], v[130:133], v[178:181], v[90:93]
	v_mfma_f32_16x16x32_bf16 v[70:73], v[114:117], v[186:189], v[70:73]
	v_mfma_f32_16x16x32_bf16 v[66:69], v[130:133], v[186:189], v[66:69]
	v_mfma_f32_16x16x32_bf16 v[162:165], v[118:121], v[154:157], v[162:165]
	v_mfma_f32_16x16x32_bf16 v[154:157], v[134:137], v[154:157], v[142:145]
	v_mfma_f32_16x16x32_bf16 v[126:129], v[118:121], v[166:169], v[126:129]
	v_mfma_f32_16x16x32_bf16 v[122:125], v[134:137], v[166:169], v[122:125]
	v_mfma_f32_16x16x32_bf16 v[94:97], v[118:121], v[182:185], v[94:97]
	v_mfma_f32_16x16x32_bf16 v[90:93], v[134:137], v[182:185], v[90:93]
	v_mfma_f32_16x16x32_bf16 v[70:73], v[118:121], v[190:193], v[70:73]
	v_mfma_f32_16x16x32_bf16 v[66:69], v[134:137], v[190:193], v[66:69]
	s_setprio 0
	s_barrier
; #define PG8_STAGE(bufoff, gbase, voff) do { _Pragma("unroll") for (int _i = 0; _i < 2; ++_i) \
;         __builtin_amdgcn_global_load_lds((const unsigned*)((const char*)(gbase) + (voff)[_i]), (PG8_LAS unsigned*)(lds + (bufoff) + ldsw + _i * 8192), 16, 0, 0); } while (0)
; #define PG8_LDA(dst, b, h) do { _Pragma("unroll") for (int m = 0; m < 4; ++m) _Pragma("unroll") for (int k = 0; k < 2; ++k) dst[m][k] = *(const PG8_LAS bf16x8*)(lds + PG8_SA(b, h) + aoff + m * 2048 + k * 1024); } while (0)
; #define PG8_MMA(ai, bj, At, Bt) do { __builtin_amdgcn_s_setprio(1); _Pragma("unroll") for (int m = 0; m < 4; ++m) _Pragma("unroll") for (int n = 0; n < 2; ++n) _Pragma("unroll") for (int k = 0; k < 2; ++k) \
;         acc[ai][bj][m][n] = __builtin_amdgcn_mfma_f32_16x16x32_bf16(Bt[n][k], At[m][k], acc[ai][bj][m][n], 0, 0, 0); __builtin_amdgcn_s_setprio(0); } while (0)
; #define PG8_WAIT_V(n) asm volatile("s_waitcnt vmcnt(" #n ")" ::: "memory")
; #define PG8_WAIT_L(n) asm volatile("s_waitcnt lgkmcnt(" #n ")" ::: "memory")
; #define PG8_BAR __builtin_amdgcn_s_barrier()
; #define PG8_SCHED __builtin_amdgcn_sched_barrier(0)
; template <class Epi, class Sched, bool ALIGN_EPI = false, bool SP2 = false>
; __device__ __forceinline__ void gemm_phase(PG8_LAS unsigned char* lds, const Gemm g, const Sched& S, const Epi& E) {
;     ...
;             PG8_LDA(At, 1, 1); PG8_STAGE(PG8_SB(1, 0), b3, voffB); PG8_STAGE(PG8_SB(1, 1), b3 + hstep, voffB); PG8_STAGE(PG8_SA(1, 0), a3, voffA);
;             PG8_WAIT_V(8); PG8_WAIT_L(0); PG8_BAR; PG8_MMA(1, 0, At, B0); PG8_MMA(1, 1, At, B1); PG8_BAR; PG8_SCHED;
	s_add_i32 s37, s37, s2
	v_lshl_add_u64 v[220:221], v[220:221], 0, s[28:29]
	s_mov_b32 m0, s37
	s_nop 0
	global_load_lds_dwordx4 v[220:221], off
	s_add_i32 m0, s37, 0x2000
	s_add_u32 s40, s40, 0x40080
	v_lshl_add_u64 v[220:221], v[222:223], 0, s[28:29]
	s_addc_u32 s41, s41, 0
	s_add_i32 s37, s51, s2
	global_load_lds_dwordx4 v[220:221], off
	v_lshl_add_u64 v[220:221], s[40:41], 0, v[208:209]
	s_mov_b32 m0, s37
	s_nop 0
	global_load_lds_dwordx4 v[220:221], off
	v_lshl_add_u64 v[220:221], s[40:41], 0, v[204:205]
	s_add_i32 m0, s37, 0x2000
	s_nop 0
	global_load_lds_dwordx4 v[220:221], off
	v_lshl_add_u64 v[220:221], v[224:225], 0, s[28:29]
	s_mov_b32 m0, s34
	s_nop 0
	global_load_lds_dwordx4 v[220:221], off
	v_lshl_add_u64 v[220:221], v[226:227], 0, s[28:29]
	s_mov_b32 m0, s35
	s_nop 0
	global_load_lds_dwordx4 v[220:221], off
	ds_read_b128 v[142:145], v250 offset:49152
	ds_read_b128 v[150:153], v250 offset:50176
	ds_read_b128 v[158:161], v250 offset:51200
	ds_read_b128 v[166:169], v250 offset:52224
	ds_read_b128 v[178:181], v250 offset:53248
	ds_read_b128 v[182:185], v250 offset:54272
	ds_read_b128 v[186:189], v250 offset:55296
	ds_read_b128 v[190:193], v250 offset:56320
	s_waitcnt vmcnt(8)
	s_waitcnt lgkmcnt(0)
	s_barrier
	s_setprio 1
	s_waitcnt lgkmcnt(0)
	v_mfma_f32_16x16x32_bf16 v[62:65], v[74:77], v[142:145], v[62:65]
	v_mfma_f32_16x16x32_bf16 v[58:61], v[98:101], v[142:145], v[58:61]
	v_mfma_f32_16x16x32_bf16 v[46:49], v[74:77], v[158:161], v[46:49]
	v_mfma_f32_16x16x32_bf16 v[42:45], v[98:101], v[158:161], v[42:45]
	v_mfma_f32_16x16x32_bf16 v[30:33], v[74:77], v[178:181], v[30:33]
	v_mfma_f32_16x16x32_bf16 v[26:29], v[98:101], v[178:181], v[26:29]
	v_mfma_f32_16x16x32_bf16 v[14:17], v[74:77], v[186:189], v[14:17]
	v_mfma_f32_16x16x32_bf16 v[10:13], v[98:101], v[186:189], v[10:13]
	v_mfma_f32_16x16x32_bf16 v[62:65], v[86:89], v[150:153], v[62:65]
	v_mfma_f32_16x16x32_bf16 v[58:61], v[102:105], v[150:153], v[58:61]
	v_mfma_f32_16x16x32_bf16 v[46:49], v[86:89], v[166:169], v[46:49]
	v_mfma_f32_16x16x32_bf16 v[42:45], v[102:105], v[166:169], v[42:45]
	v_mfma_f32_16x16x32_bf16 v[30:33], v[86:89], v[182:185], v[30:33]
	v_mfma_f32_16x16x32_bf16 v[26:29], v[102:105], v[182:185], v[26:29]
	v_mfma_f32_16x16x32_bf16 v[14:17], v[86:89], v[190:193], v[14:17]
	v_mfma_f32_16x16x32_bf16 v[10:13], v[102:105], v[190:193], v[10:13]
	s_setprio 0
	s_setprio 1
	v_mfma_f32_16x16x32_bf16 v[54:57], v[114:117], v[142:145], v[54:57]
	v_mfma_f32_16x16x32_bf16 v[50:53], v[130:133], v[142:145], v[50:53]
	v_mfma_f32_16x16x32_bf16 v[38:41], v[114:117], v[158:161], v[38:41]
	v_mfma_f32_16x16x32_bf16 v[34:37], v[130:133], v[158:161], v[34:37]
	v_mfma_f32_16x16x32_bf16 v[22:25], v[114:117], v[178:181], v[22:25]
	v_mfma_f32_16x16x32_bf16 v[18:21], v[130:133], v[178:181], v[18:21]
	v_mfma_f32_16x16x32_bf16 v[6:9], v[114:117], v[186:189], v[6:9]
	v_mfma_f32_16x16x32_bf16 v[2:5], v[130:133], v[186:189], v[2:5]
	v_mfma_f32_16x16x32_bf16 v[54:57], v[118:121], v[150:153], v[54:57]
	v_mfma_f32_16x16x32_bf16 v[50:53], v[134:137], v[150:153], v[50:53]
	v_mfma_f32_16x16x32_bf16 v[38:41], v[118:121], v[166:169], v[38:41]
	v_mfma_f32_16x16x32_bf16 v[34:37], v[134:137], v[166:169], v[34:37]
	v_mfma_f32_16x16x32_bf16 v[22:25], v[118:121], v[182:185], v[22:25]
	v_mfma_f32_16x16x32_bf16 v[18:21], v[134:137], v[182:185], v[18:21]
	v_mfma_f32_16x16x32_bf16 v[6:9], v[118:121], v[190:193], v[6:9]
	v_mfma_f32_16x16x32_bf16 v[2:5], v[134:137], v[190:193], v[2:5]
	s_setprio 0
	s_barrier
	s_add_i32 s50, s50, 2
	s_add_u32 s20, s20, 0x100
	s_addc_u32 s21, s21, 0
	s_add_u32 s48, s48, 0x100
	s_addc_u32 s49, s49, 0
	s_cmp_gt_u32 s50, 13
	s_cbranch_scc0 .LBB0_478
	s_and_b64 vcc, exec, s[4:5]
	s_cbranch_vccz .LBB0_481
	s_barrier

; #define PG8_STAGE(bufoff, gbase, voff) do { _Pragma("unroll") for (int _i = 0; _i < 2; ++_i) \
;         __builtin_amdgcn_global_load_lds((const unsigned*)((const char*)(gbase) + (voff)[_i]), (PG8_LAS unsigned*)(lds + (bufoff) + ldsw + _i * 8192), 16, 0, 0); } while (0)
; #define PG8_LDA(dst, b, h) do { _Pragma("unroll") for (int m = 0; m < 4; ++m) _Pragma("unroll") for (int k = 0; k < 2; ++k) dst[m][k] = *(const PG8_LAS bf16x8*)(lds + PG8_SA(b, h) + aoff + m * 2048 + k * 1024); } while (0)
; #define PG8_LDB(dst, b, h) do { _Pragma("unroll") for (int n = 0; n < 2; ++n) _Pragma("unroll") for (int k = 0; k < 2; ++k) dst[n][k] = *(const PG8_LAS bf16x8*)(lds + PG8_SB(b, h) + boff + n * 2048 + k * 1024); } while (0)
; #define PG8_MMA(ai, bj, At, Bt) do { __builtin_amdgcn_s_setprio(1); _Pragma("unroll") for (int m = 0; m < 4; ++m) _Pragma("unroll") for (int n = 0; n < 2; ++n) _Pragma("unroll") for (int k = 0; k < 2; ++k) \
;         acc[ai][bj][m][n] = __builtin_amdgcn_mfma_f32_16x16x32_bf16(Bt[n][k], At[m][k], acc[ai][bj][m][n], 0, 0, 0); __builtin_amdgcn_s_setprio(0); } while (0)
; #define PG8_WAIT_V(n) asm volatile("s_waitcnt vmcnt(" #n ")" ::: "memory")
; #define PG8_WAIT_L(n) asm volatile("s_waitcnt lgkmcnt(" #n ")" ::: "memory")
; template <class Epi, class Sched, bool ALIGN_EPI = false, bool SP2 = false>
; __device__ __forceinline__ void gemm_phase(PG8_LAS unsigned char* lds, const Gemm g, const Sched& S, const Epi& E) {
;     ...
;             const bool last = (t == nt - 2);
;             const char* a1 = cA + (size_t)(t + 1) * kstep;
;             const char* a2 = last ? nA : cA + (size_t)(t + 2) * kstep; const char* b2 = last ? nB : cB + (size_t)(t + 2) * kstep;
;             const char* a3 = a2 + kstep; const char* b3 = b2 + kstep;
;             if (last && has_next) S.a_ready(nxt);
;             if constexpr (SP2) {
;             PG8_LDB(B0, 0, 0); PG8_LDB(B1, 0, 1); PG8_SCHED; PG8_LDA(At, 0, 0); PG8_STAGE(PG8_SA(1, 1), a1 + hstep, voffA);
;             PG8_WAIT_V(8); PG8_WAIT_L(0); PG8_BAR; PG8_MMA(0, 0, At, B0); PG8_MMA(0, 1, At, B1); PG8_BAR; PG8_SCHED;
;             PG8_LDA(At, 0, 1); PG8_STAGE(PG8_SB(0, 0), b2, voffB); PG8_STAGE(PG8_SB(0, 1), b2 + hstep, voffB); PG8_STAGE(PG8_SA(0, 0), a2, voffA);
;             PG8_WAIT_V(8); PG8_WAIT_L(0); PG8_BAR; PG8_MMA(1, 0, At, B0); PG8_MMA(1, 1, At, B1); PG8_BAR; PG8_SCHED;
.LBB0_558:
	s_add_u32 s37, s20, 0xfffc0080
	s_addc_u32 s42, s21, -1
	s_add_i32 s53, 0, 0x10000
	s_cmp_eq_u32 s52, 12
	s_cselect_b32 s45, s9, s42
	s_cselect_b32 s44, s48, s37
	s_cselect_b32 s43, s7, s51
	s_cselect_b32 s42, s49, s50
	s_add_i32 s37, 0, 0x14000
	v_lshl_add_u64 v[156:157], s[20:21], 0, v[136:137]
	s_add_i32 m0, s3, 0xc000
	s_nop 0
	global_load_lds_dwordx4 v[156:157], off
	v_lshl_add_u64 v[156:157], s[20:21], 0, v[138:139]
	s_add_i32 m0, s3, 0xe000
	s_nop 0
	global_load_lds_dwordx4 v[156:157], off
	v_add_u32_e32 v152, s53, v160
	v_add_u32_e32 v156, s37, v160
	ds_read_b128 v[140:143], v152
	ds_read_b128 v[144:147], v152 offset:1024
	ds_read_b128 v[148:151], v152 offset:2048
	ds_read_b128 v[152:155], v152 offset:3072
	ds_read_b128 v[164:167], v156
	ds_read_b128 v[168:171], v156 offset:1024
	ds_read_b128 v[172:175], v156 offset:2048
	ds_read_b128 v[176:179], v156 offset:3072
	ds_read_b128 v[180:183], v162
	ds_read_b128 v[184:187], v162 offset:1024
	ds_read_b128 v[188:191], v162 offset:2048
	ds_read_b128 v[204:207], v162 offset:3072
	ds_read_b128 v[208:211], v162 offset:4096
	ds_read_b128 v[212:215], v162 offset:5120
	ds_read_b128 v[216:219], v162 offset:6144
	ds_read_b128 v[220:223], v162 offset:7168
	s_waitcnt vmcnt(8)
	s_waitcnt lgkmcnt(0)
	s_barrier
	s_setprio 1
	s_waitcnt lgkmcnt(0)
	v_mfma_f32_16x16x32_bf16 v[126:129], v[140:143], v[180:183], v[126:129]
	v_mfma_f32_16x16x32_bf16 v[94:97], v[148:151], v[180:183], v[94:97]
	v_mfma_f32_16x16x32_bf16 v[122:125], v[140:143], v[188:191], v[122:125]
	v_mfma_f32_16x16x32_bf16 v[90:93], v[148:151], v[188:191], v[90:93]
	v_mfma_f32_16x16x32_bf16 v[118:121], v[140:143], v[208:211], v[118:121]
	v_mfma_f32_16x16x32_bf16 v[86:89], v[148:151], v[208:211], v[86:89]
	v_mfma_f32_16x16x32_bf16 v[114:117], v[140:143], v[216:219], v[114:117]
	v_mfma_f32_16x16x32_bf16 v[82:85], v[148:151], v[216:219], v[82:85]
	v_mfma_f32_16x16x32_bf16 v[126:129], v[144:147], v[184:187], v[126:129]
	v_mfma_f32_16x16x32_bf16 v[94:97], v[152:155], v[184:187], v[94:97]
	v_mfma_f32_16x16x32_bf16 v[122:125], v[144:147], v[204:207], v[122:125]
	v_mfma_f32_16x16x32_bf16 v[90:93], v[152:155], v[204:207], v[90:93]
	v_mfma_f32_16x16x32_bf16 v[118:121], v[144:147], v[212:215], v[118:121]
	v_mfma_f32_16x16x32_bf16 v[86:89], v[152:155], v[212:215], v[86:89]
	v_mfma_f32_16x16x32_bf16 v[114:117], v[144:147], v[220:223], v[114:117]
	v_mfma_f32_16x16x32_bf16 v[82:85], v[152:155], v[220:223], v[82:85]
	s_setprio 0
	s_setprio 1
	v_mfma_f32_16x16x32_bf16 v[62:65], v[164:167], v[180:183], v[62:65]
	v_mfma_f32_16x16x32_bf16 v[30:33], v[172:175], v[180:183], v[30:33]
	v_mfma_f32_16x16x32_bf16 v[58:61], v[164:167], v[188:191], v[58:61]
	v_mfma_f32_16x16x32_bf16 v[26:29], v[172:175], v[188:191], v[26:29]
	v_mfma_f32_16x16x32_bf16 v[54:57], v[164:167], v[208:211], v[54:57]
	v_mfma_f32_16x16x32_bf16 v[22:25], v[172:175], v[208:211], v[22:25]
	v_mfma_f32_16x16x32_bf16 v[50:53], v[164:167], v[216:219], v[50:53]
	v_mfma_f32_16x16x32_bf16 v[18:21], v[172:175], v[216:219], v[18:21]
	v_mfma_f32_16x16x32_bf16 v[62:65], v[168:171], v[184:187], v[62:65]
	v_mfma_f32_16x16x32_bf16 v[30:33], v[176:179], v[184:187], v[30:33]
	v_mfma_f32_16x16x32_bf16 v[58:61], v[168:171], v[204:207], v[58:61]
	v_mfma_f32_16x16x32_bf16 v[26:29], v[176:179], v[204:207], v[26:29]
	v_mfma_f32_16x16x32_bf16 v[54:57], v[168:171], v[212:215], v[54:57]
	v_mfma_f32_16x16x32_bf16 v[22:25], v[176:179], v[212:215], v[22:25]
	v_mfma_f32_16x16x32_bf16 v[50:53], v[168:171], v[220:223], v[50:53]
	v_mfma_f32_16x16x32_bf16 v[18:21], v[176:179], v[220:223], v[18:21]
	s_setprio 0
	s_barrier
	s_add_i32 s53, s53, s2
	v_lshl_add_u64 v[156:157], s[42:43], 0, v[0:1]
	s_mov_b32 m0, s53
	s_nop 0
	global_load_lds_dwordx4 v[156:157], off
	s_add_i32 m0, s53, 0x2000
	s_add_u32 s54, s42, 0x40000
	v_lshl_add_u64 v[192:193], s[42:43], 0, v[130:131]
	s_addc_u32 s55, s43, 0
	s_add_i32 s37, s37, s2
	global_load_lds_dwordx4 v[192:193], off
	v_lshl_add_u64 v[194:195], s[54:55], 0, v[0:1]
	s_mov_b32 m0, s37
	v_lshl_add_u64 v[224:225], s[44:45], 0, v[132:133]
	global_load_lds_dwordx4 v[194:195], off
	v_lshl_add_u64 v[194:195], s[54:55], 0, v[130:131]
	s_add_i32 m0, s37, 0x2000
	s_nop 0
	global_load_lds_dwordx4 v[194:195], off
	v_lshl_add_u64 v[194:195], s[44:45], 0, v[134:135]
	s_mov_b32 m0, s3
	s_nop 0
	global_load_lds_dwordx4 v[194:195], off
	s_mov_b32 m0, s16
	s_nop 0
	global_load_lds_dwordx4 v[224:225], off
	ds_read_b128 v[180:183], v162 offset:16384
	ds_read_b128 v[184:187], v162 offset:17408
	ds_read_b128 v[188:191], v162 offset:18432
	ds_read_b128 v[204:207], v162 offset:19456
	ds_read_b128 v[208:211], v162 offset:20480
	ds_read_b128 v[212:215], v162 offset:21504
	ds_read_b128 v[216:219], v162 offset:22528
	ds_read_b128 v[220:223], v162 offset:23552
	s_waitcnt vmcnt(8)
	s_waitcnt lgkmcnt(0)
	s_barrier
; #define PG8_STAGE(bufoff, gbase, voff) do { _Pragma("unroll") for (int _i = 0; _i < 2; ++_i) \
;         __builtin_amdgcn_global_load_lds((const unsigned*)((const char*)(gbase) + (voff)[_i]), (PG8_LAS unsigned*)(lds + (bufoff) + ldsw + _i * 8192), 16, 0, 0); } while (0)
; #define PG8_LDA(dst, b, h) do { _Pragma("unroll") for (int m = 0; m < 4; ++m) _Pragma("unroll") for (int k = 0; k < 2; ++k) dst[m][k] = *(const PG8_LAS bf16x8*)(lds + PG8_SA(b, h) + aoff + m * 2048 + k * 1024); } while (0)
; #define PG8_LDB(dst, b, h) do { _Pragma("unroll") for (int n = 0; n < 2; ++n) _Pragma("unroll") for (int k = 0; k < 2; ++k) dst[n][k] = *(const PG8_LAS bf16x8*)(lds + PG8_SB(b, h) + boff + n * 2048 + k * 1024); } while (0)
; #define PG8_MMA(ai, bj, At, Bt) do { __builtin_amdgcn_s_setprio(1); _Pragma("unroll") for (int m = 0; m < 4; ++m) _Pragma("unroll") for (int n = 0; n < 2; ++n) _Pragma("unroll") for (int k = 0; k < 2; ++k) \
;         acc[ai][bj][m][n] = __builtin_amdgcn_mfma_f32_16x16x32_bf16(Bt[n][k], At[m][k], acc[ai][bj][m][n], 0, 0, 0); __builtin_amdgcn_s_setprio(0); } while (0)
; #define PG8_WAIT_V(n) asm volatile("s_waitcnt vmcnt(" #n ")" ::: "memory")
; #define PG8_WAIT_L(n) asm volatile("s_waitcnt lgkmcnt(" #n ")" ::: "memory")
; #define PG8_BAR __builtin_amdgcn_s_barrier()
; #define PG8_SCHED __builtin_amdgcn_sched_barrier(0)
; template <class Epi, class Sched, bool ALIGN_EPI = false, bool SP2 = false>
; __device__ __forceinline__ void gemm_phase(PG8_LAS unsigned char* lds, const Gemm g, const Sched& S, const Epi& E) {
;     ...
;             PG8_WAIT_V(8); PG8_WAIT_L(0); PG8_BAR; PG8_MMA(1, 0, At, B0); PG8_MMA(1, 1, At, B1); PG8_BAR; PG8_SCHED;
;             PG8_LDB(B0, 1, 0); PG8_LDB(B1, 1, 1); PG8_SCHED; PG8_LDA(At, 1, 0); PG8_STAGE(PG8_SA(0, 1), a2 + hstep, voffA);
;             PG8_WAIT_V(8); PG8_WAIT_L(0); PG8_BAR; PG8_MMA(0, 0, At, B0); PG8_MMA(0, 1, At, B1); PG8_BAR; PG8_SCHED;
	s_setprio 1
	s_waitcnt lgkmcnt(0)
	v_mfma_f32_16x16x32_bf16 v[110:113], v[140:143], v[180:183], v[110:113]
	v_mfma_f32_16x16x32_bf16 v[78:81], v[148:151], v[180:183], v[78:81]
	v_mfma_f32_16x16x32_bf16 v[106:109], v[140:143], v[188:191], v[106:109]
	v_mfma_f32_16x16x32_bf16 v[74:77], v[148:151], v[188:191], v[74:77]
	v_mfma_f32_16x16x32_bf16 v[102:105], v[140:143], v[208:211], v[102:105]
	v_mfma_f32_16x16x32_bf16 v[70:73], v[148:151], v[208:211], v[70:73]
	v_mfma_f32_16x16x32_bf16 v[98:101], v[140:143], v[216:219], v[98:101]
	v_mfma_f32_16x16x32_bf16 v[66:69], v[148:151], v[216:219], v[66:69]
	v_mfma_f32_16x16x32_bf16 v[110:113], v[144:147], v[184:187], v[110:113]
	v_mfma_f32_16x16x32_bf16 v[78:81], v[152:155], v[184:187], v[78:81]
	v_mfma_f32_16x16x32_bf16 v[106:109], v[144:147], v[204:207], v[106:109]
	v_mfma_f32_16x16x32_bf16 v[74:77], v[152:155], v[204:207], v[74:77]
	v_mfma_f32_16x16x32_bf16 v[102:105], v[144:147], v[212:215], v[102:105]
	v_mfma_f32_16x16x32_bf16 v[70:73], v[152:155], v[212:215], v[70:73]
	v_mfma_f32_16x16x32_bf16 v[98:101], v[144:147], v[220:223], v[98:101]
	v_mfma_f32_16x16x32_bf16 v[66:69], v[152:155], v[220:223], v[66:69]
	s_setprio 0
	s_setprio 1
	v_mfma_f32_16x16x32_bf16 v[46:49], v[164:167], v[180:183], v[46:49]
	v_mfma_f32_16x16x32_bf16 v[14:17], v[172:175], v[180:183], v[14:17]
	v_mfma_f32_16x16x32_bf16 v[42:45], v[164:167], v[188:191], v[42:45]
	v_mfma_f32_16x16x32_bf16 v[10:13], v[172:175], v[188:191], v[10:13]
	v_mfma_f32_16x16x32_bf16 v[38:41], v[164:167], v[208:211], v[38:41]
	v_mfma_f32_16x16x32_bf16 v[6:9], v[172:175], v[208:211], v[6:9]
	v_mfma_f32_16x16x32_bf16 v[34:37], v[164:167], v[216:219], v[34:37]
	v_mfma_f32_16x16x32_bf16 v[2:5], v[172:175], v[216:219], v[2:5]
	v_mfma_f32_16x16x32_bf16 v[46:49], v[168:171], v[184:187], v[46:49]
	v_mfma_f32_16x16x32_bf16 v[14:17], v[176:179], v[184:187], v[14:17]
	v_mfma_f32_16x16x32_bf16 v[42:45], v[168:171], v[204:207], v[42:45]
	v_mfma_f32_16x16x32_bf16 v[10:13], v[176:179], v[204:207], v[10:13]
	v_mfma_f32_16x16x32_bf16 v[38:41], v[168:171], v[212:215], v[38:41]
	v_mfma_f32_16x16x32_bf16 v[6:9], v[176:179], v[212:215], v[6:9]
	v_mfma_f32_16x16x32_bf16 v[34:37], v[168:171], v[220:223], v[34:37]
	v_mfma_f32_16x16x32_bf16 v[2:5], v[176:179], v[220:223], v[2:5]
	s_setprio 0
	s_barrier
	s_add_i32 s37, 0, 0x18000
	s_add_i32 s53, 0, 0x1c000
	s_add_u32 s44, s44, 0x40000
	s_addc_u32 s45, s45, 0
	s_mov_b32 m0, s18
	v_lshl_add_u64 v[226:227], s[44:45], 0, v[134:135]
	global_load_lds_dwordx4 v[226:227], off
	v_lshl_add_u64 v[226:227], s[44:45], 0, v[132:133]
	s_mov_b32 m0, s19
	s_nop 0
	global_load_lds_dwordx4 v[226:227], off
	v_add_u32_e32 v152, s37, v160
	v_add_u32_e32 v163, s53, v160
	ds_read_b128 v[140:143], v152
	ds_read_b128 v[144:147], v152 offset:1024
	ds_read_b128 v[148:151], v152 offset:2048
	ds_read_b128 v[152:155], v152 offset:3072
	ds_read_b128 v[164:167], v163
	ds_read_b128 v[168:171], v163 offset:1024
	ds_read_b128 v[172:175], v163 offset:2048
	ds_read_b128 v[176:179], v163 offset:3072
	ds_read_b128 v[180:183], v162 offset:32768
	ds_read_b128 v[184:187], v162 offset:33792
	ds_read_b128 v[188:191], v162 offset:34816
	ds_read_b128 v[204:207], v162 offset:35840
	ds_read_b128 v[208:211], v162 offset:36864
	ds_read_b128 v[212:215], v162 offset:37888
	ds_read_b128 v[216:219], v162 offset:38912
	ds_read_b128 v[220:223], v162 offset:39936
	s_waitcnt vmcnt(8)
	s_waitcnt lgkmcnt(0)
	s_barrier
	s_setprio 1
	s_waitcnt lgkmcnt(0)
	v_mfma_f32_16x16x32_bf16 v[126:129], v[140:143], v[180:183], v[126:129]
	v_mfma_f32_16x16x32_bf16 v[94:97], v[148:151], v[180:183], v[94:97]
	v_mfma_f32_16x16x32_bf16 v[122:125], v[140:143], v[188:191], v[122:125]
	v_mfma_f32_16x16x32_bf16 v[90:93], v[148:151], v[188:191], v[90:93]
	v_mfma_f32_16x16x32_bf16 v[118:121], v[140:143], v[208:211], v[118:121]
	v_mfma_f32_16x16x32_bf16 v[86:89], v[148:151], v[208:211], v[86:89]
	v_mfma_f32_16x16x32_bf16 v[114:117], v[140:143], v[216:219], v[114:117]
	v_mfma_f32_16x16x32_bf16 v[82:85], v[148:151], v[216:219], v[82:85]
	v_mfma_f32_16x16x32_bf16 v[126:129], v[144:147], v[184:187], v[126:129]
	v_mfma_f32_16x16x32_bf16 v[94:97], v[152:155], v[184:187], v[94:97]
	v_mfma_f32_16x16x32_bf16 v[122:125], v[144:147], v[204:207], v[122:125]
	v_mfma_f32_16x16x32_bf16 v[90:93], v[152:155], v[204:207], v[90:93]
	v_mfma_f32_16x16x32_bf16 v[118:121], v[144:147], v[212:215], v[118:121]
	v_mfma_f32_16x16x32_bf16 v[86:89], v[152:155], v[212:215], v[86:89]
	v_mfma_f32_16x16x32_bf16 v[114:117], v[144:147], v[220:223], v[114:117]
	v_mfma_f32_16x16x32_bf16 v[82:85], v[152:155], v[220:223], v[82:85]
	s_setprio 0
	s_setprio 1
	v_mfma_f32_16x16x32_bf16 v[62:65], v[164:167], v[180:183], v[62:65]
	v_mfma_f32_16x16x32_bf16 v[30:33], v[172:175], v[180:183], v[30:33]
	v_mfma_f32_16x16x32_bf16 v[58:61], v[164:167], v[188:191], v[58:61]
	v_mfma_f32_16x16x32_bf16 v[26:29], v[172:175], v[188:191], v[26:29]
	v_mfma_f32_16x16x32_bf16 v[54:57], v[164:167], v[208:211], v[54:57]
	v_mfma_f32_16x16x32_bf16 v[22:25], v[172:175], v[208:211], v[22:25]
	v_mfma_f32_16x16x32_bf16 v[50:53], v[164:167], v[216:219], v[50:53]
	v_mfma_f32_16x16x32_bf16 v[18:21], v[172:175], v[216:219], v[18:21]
	v_mfma_f32_16x16x32_bf16 v[62:65], v[168:171], v[184:187], v[62:65]
	v_mfma_f32_16x16x32_bf16 v[30:33], v[176:179], v[184:187], v[30:33]
	v_mfma_f32_16x16x32_bf16 v[58:61], v[168:171], v[204:207], v[58:61]
	v_mfma_f32_16x16x32_bf16 v[26:29], v[176:179], v[204:207], v[26:29]
	v_mfma_f32_16x16x32_bf16 v[54:57], v[168:171], v[212:215], v[54:57]
	v_mfma_f32_16x16x32_bf16 v[22:25], v[176:179], v[212:215], v[22:25]
	v_mfma_f32_16x16x32_bf16 v[50:53], v[168:171], v[220:223], v[50:53]
	v_mfma_f32_16x16x32_bf16 v[18:21], v[176:179], v[220:223], v[18:21]
	s_setprio 0
	s_barrier
; #define PG8_STAGE(bufoff, gbase, voff) do { _Pragma("unroll") for (int _i = 0; _i < 2; ++_i) \
;         __builtin_amdgcn_global_load_lds((const unsigned*)((const char*)(gbase) + (voff)[_i]), (PG8_LAS unsigned*)(lds + (bufoff) + ldsw + _i * 8192), 16, 0, 0); } while (0)
; #define PG8_LDA(dst, b, h) do { _Pragma("unroll") for (int m = 0; m < 4; ++m) _Pragma("unroll") for (int k = 0; k < 2; ++k) dst[m][k] = *(const PG8_LAS bf16x8*)(lds + PG8_SA(b, h) + aoff + m * 2048 + k * 1024); } while (0)
; #define PG8_MMA(ai, bj, At, Bt) do { __builtin_amdgcn_s_setprio(1); _Pragma("unroll") for (int m = 0; m < 4; ++m) _Pragma("unroll") for (int n = 0; n < 2; ++n) _Pragma("unroll") for (int k = 0; k < 2; ++k) \
;         acc[ai][bj][m][n] = __builtin_amdgcn_mfma_f32_16x16x32_bf16(Bt[n][k], At[m][k], acc[ai][bj][m][n], 0, 0, 0); __builtin_amdgcn_s_setprio(0); } while (0)
; #define PG8_WAIT_V(n) asm volatile("s_waitcnt vmcnt(" #n ")" ::: "memory")
; #define PG8_WAIT_L(n) asm volatile("s_waitcnt lgkmcnt(" #n ")" ::: "memory")
; #define PG8_BAR __builtin_amdgcn_s_barrier()
; #define PG8_SCHED __builtin_amdgcn_sched_barrier(0)
; template <class Epi, class Sched, bool ALIGN_EPI = false, bool SP2 = false>
; __device__ __forceinline__ void gemm_phase(PG8_LAS unsigned char* lds, const Gemm g, const Sched& S, const Epi& E) {
;     ...
;             PG8_LDA(At, 1, 1); PG8_STAGE(PG8_SB(1, 0), b3, voffB); PG8_STAGE(PG8_SB(1, 1), b3 + hstep, voffB); PG8_STAGE(PG8_SA(1, 0), a3, voffA);
;             PG8_WAIT_V(8); PG8_WAIT_L(0); PG8_BAR; PG8_MMA(1, 0, At, B0); PG8_MMA(1, 1, At, B1); PG8_BAR; PG8_SCHED;
	s_add_i32 s37, s37, s2
	v_lshl_add_u64 v[156:157], v[156:157], 0, s[28:29]
	s_mov_b32 m0, s37
	s_nop 0
	global_load_lds_dwordx4 v[156:157], off
	s_add_i32 m0, s37, 0x2000
	s_add_u32 s42, s42, 0x40080
	v_lshl_add_u64 v[156:157], v[192:193], 0, s[28:29]
	s_addc_u32 s43, s43, 0
	s_add_i32 s37, s53, s2
	global_load_lds_dwordx4 v[156:157], off
	v_lshl_add_u64 v[156:157], s[42:43], 0, v[0:1]
	s_mov_b32 m0, s37
	s_nop 0
	global_load_lds_dwordx4 v[156:157], off
	v_lshl_add_u64 v[156:157], s[42:43], 0, v[130:131]
	s_add_i32 m0, s37, 0x2000
	s_nop 0
	global_load_lds_dwordx4 v[156:157], off
	v_lshl_add_u64 v[156:157], v[194:195], 0, s[28:29]
	s_mov_b32 m0, s34
	s_nop 0
	global_load_lds_dwordx4 v[156:157], off
	v_lshl_add_u64 v[156:157], v[224:225], 0, s[28:29]
	s_mov_b32 m0, s35
	s_nop 0
	global_load_lds_dwordx4 v[156:157], off
	ds_read_b128 v[180:183], v162 offset:49152
	ds_read_b128 v[184:187], v162 offset:50176
	ds_read_b128 v[188:191], v162 offset:51200
	ds_read_b128 v[204:207], v162 offset:52224
	ds_read_b128 v[208:211], v162 offset:53248
	ds_read_b128 v[212:215], v162 offset:54272
	ds_read_b128 v[216:219], v162 offset:55296
	ds_read_b128 v[220:223], v162 offset:56320
	s_waitcnt vmcnt(8)
	s_waitcnt lgkmcnt(0)
	s_barrier
	s_setprio 1
	s_waitcnt lgkmcnt(0)
	v_mfma_f32_16x16x32_bf16 v[110:113], v[140:143], v[180:183], v[110:113]
	v_mfma_f32_16x16x32_bf16 v[78:81], v[148:151], v[180:183], v[78:81]
	v_mfma_f32_16x16x32_bf16 v[106:109], v[140:143], v[188:191], v[106:109]
	v_mfma_f32_16x16x32_bf16 v[74:77], v[148:151], v[188:191], v[74:77]
	v_mfma_f32_16x16x32_bf16 v[102:105], v[140:143], v[208:211], v[102:105]
	v_mfma_f32_16x16x32_bf16 v[70:73], v[148:151], v[208:211], v[70:73]
	v_mfma_f32_16x16x32_bf16 v[98:101], v[140:143], v[216:219], v[98:101]
	v_mfma_f32_16x16x32_bf16 v[66:69], v[148:151], v[216:219], v[66:69]
	v_mfma_f32_16x16x32_bf16 v[110:113], v[144:147], v[184:187], v[110:113]
	v_mfma_f32_16x16x32_bf16 v[78:81], v[152:155], v[184:187], v[78:81]
	v_mfma_f32_16x16x32_bf16 v[106:109], v[144:147], v[204:207], v[106:109]
	v_mfma_f32_16x16x32_bf16 v[74:77], v[152:155], v[204:207], v[74:77]
	v_mfma_f32_16x16x32_bf16 v[102:105], v[144:147], v[212:215], v[102:105]
	v_mfma_f32_16x16x32_bf16 v[70:73], v[152:155], v[212:215], v[70:73]
	v_mfma_f32_16x16x32_bf16 v[98:101], v[144:147], v[220:223], v[98:101]
	v_mfma_f32_16x16x32_bf16 v[66:69], v[152:155], v[220:223], v[66:69]
	s_setprio 0
	s_setprio 1
	v_mfma_f32_16x16x32_bf16 v[46:49], v[164:167], v[180:183], v[46:49]
	v_mfma_f32_16x16x32_bf16 v[14:17], v[172:175], v[180:183], v[14:17]
	v_mfma_f32_16x16x32_bf16 v[42:45], v[164:167], v[188:191], v[42:45]
	v_mfma_f32_16x16x32_bf16 v[10:13], v[172:175], v[188:191], v[10:13]
	v_mfma_f32_16x16x32_bf16 v[38:41], v[164:167], v[208:211], v[38:41]
	v_mfma_f32_16x16x32_bf16 v[6:9], v[172:175], v[208:211], v[6:9]
	v_mfma_f32_16x16x32_bf16 v[34:37], v[164:167], v[216:219], v[34:37]
	v_mfma_f32_16x16x32_bf16 v[2:5], v[172:175], v[216:219], v[2:5]
	v_mfma_f32_16x16x32_bf16 v[46:49], v[168:171], v[184:187], v[46:49]
	v_mfma_f32_16x16x32_bf16 v[14:17], v[176:179], v[184:187], v[14:17]
	v_mfma_f32_16x16x32_bf16 v[42:45], v[168:171], v[204:207], v[42:45]
	v_mfma_f32_16x16x32_bf16 v[10:13], v[176:179], v[204:207], v[10:13]
	v_mfma_f32_16x16x32_bf16 v[38:41], v[168:171], v[212:215], v[38:41]
	v_mfma_f32_16x16x32_bf16 v[6:9], v[176:179], v[212:215], v[6:9]
	v_mfma_f32_16x16x32_bf16 v[34:37], v[168:171], v[220:223], v[34:37]
	v_mfma_f32_16x16x32_bf16 v[2:5], v[176:179], v[220:223], v[2:5]
	s_setprio 0
	s_barrier
	s_add_i32 s52, s52, 2
	s_add_u32 s20, s20, 0x100
	s_addc_u32 s21, s21, 0
	s_add_u32 s50, s50, 0x100
	s_addc_u32 s51, s51, 0
	s_cmp_gt_u32 s52, 13
	s_cbranch_scc0 .LBB0_558
	s_and_b64 vcc, exec, s[4:5]
	s_cbranch_vccz .LBB0_561
	s_barrier

; #define PG8_STAGE(bufoff, gbase, voff) do { _Pragma("unroll") for (int _i = 0; _i < 2; ++_i) \
;         __builtin_amdgcn_global_load_lds((const unsigned*)((const char*)(gbase) + (voff)[_i]), (PG8_LAS unsigned*)(lds + (bufoff) + ldsw + _i * 8192), 16, 0, 0); } while (0)
; #define PG8_LDA(dst, b, h) do { _Pragma("unroll") for (int m = 0; m < 4; ++m) _Pragma("unroll") for (int k = 0; k < 2; ++k) dst[m][k] = *(const PG8_LAS bf16x8*)(lds + PG8_SA(b, h) + aoff + m * 2048 + k * 1024); } while (0)
; #define PG8_LDB(dst, b, h) do { _Pragma("unroll") for (int n = 0; n < 2; ++n) _Pragma("unroll") for (int k = 0; k < 2; ++k) dst[n][k] = *(const PG8_LAS bf16x8*)(lds + PG8_SB(b, h) + boff + n * 2048 + k * 1024); } while (0)
; #define PG8_MMA(ai, bj, At, Bt) do { __builtin_amdgcn_s_setprio(1); _Pragma("unroll") for (int m = 0; m < 4; ++m) _Pragma("unroll") for (int n = 0; n < 2; ++n) _Pragma("unroll") for (int k = 0; k < 2; ++k) \
;         acc[ai][bj][m][n] = __builtin_amdgcn_mfma_f32_16x16x32_bf16(Bt[n][k], At[m][k], acc[ai][bj][m][n], 0, 0, 0); __builtin_amdgcn_s_setprio(0); } while (0)
; #define PG8_WAIT_V(n) asm volatile("s_waitcnt vmcnt(" #n ")" ::: "memory")
; #define PG8_WAIT_L(n) asm volatile("s_waitcnt lgkmcnt(" #n ")" ::: "memory")
; template <class Epi, class Sched, bool ALIGN_EPI = false, bool SP2 = false>
; __device__ __forceinline__ void gemm_phase(PG8_LAS unsigned char* lds, const Gemm g, const Sched& S, const Epi& E) {
;     ...
;             const bool last = (t == nt - 2);
;             const char* a1 = cA + (size_t)(t + 1) * kstep;
;             const char* a2 = last ? nA : cA + (size_t)(t + 2) * kstep; const char* b2 = last ? nB : cB + (size_t)(t + 2) * kstep;
;             const char* a3 = a2 + kstep; const char* b3 = b2 + kstep;
;             if (last && has_next) S.a_ready(nxt);
;             if constexpr (SP2) {
;             PG8_LDB(B0, 0, 0); PG8_LDB(B1, 0, 1); PG8_SCHED; PG8_LDA(At, 0, 0); PG8_STAGE(PG8_SA(1, 1), a1 + hstep, voffA);
;             PG8_WAIT_V(8); PG8_WAIT_L(0); PG8_BAR; PG8_MMA(0, 0, At, B0); PG8_MMA(0, 1, At, B1); PG8_BAR; PG8_SCHED;
;             PG8_LDA(At, 0, 1); PG8_STAGE(PG8_SB(0, 0), b2, voffB); PG8_STAGE(PG8_SB(0, 1), b2 + hstep, voffB); PG8_STAGE(PG8_SA(0, 0), a2, voffA);
;             PG8_WAIT_V(8); PG8_WAIT_L(0); PG8_BAR; PG8_MMA(1, 0, At, B0); PG8_MMA(1, 1, At, B1); PG8_BAR; PG8_SCHED;
.LBB0_918:
	s_add_u32 s20, s8, 0xfffc0080
	s_addc_u32 s21, s9, -1
	s_add_i32 s37, 0, 0x10000
	s_cmp_eq_u32 s55, 12
	s_cselect_b32 s51, s36, s21
	s_cselect_b32 s50, s45, s20
	s_cselect_b32 s21, s27, s54
	s_cselect_b32 s20, s52, s53
	s_add_i32 s58, 0, 0x14000
	v_lshl_add_u64 v[192:193], s[8:9], 0, v[144:145]
	s_add_i32 m0, s3, 0xc000
	s_nop 0
	global_load_lds_dwordx4 v[192:193], off
	v_lshl_add_u64 v[192:193], s[8:9], 0, v[146:147]
	s_add_i32 m0, s3, 0xe000
	s_nop 0
	global_load_lds_dwordx4 v[192:193], off
	v_add_u32_e32 v152, s37, v157
	v_add_u32_e32 v163, s58, v157
	ds_read_b128 v[130:133], v152
	ds_read_b128 v[134:137], v152 offset:1024
	ds_read_b128 v[148:151], v152 offset:2048
	ds_read_b128 v[152:155], v152 offset:3072
	ds_read_b128 v[164:167], v163
	ds_read_b128 v[168:171], v163 offset:1024
	ds_read_b128 v[172:175], v163 offset:2048
	ds_read_b128 v[176:179], v163 offset:3072
	ds_read_b128 v[180:183], v161
	ds_read_b128 v[184:187], v161 offset:1024
	ds_read_b128 v[188:191], v161 offset:2048
	ds_read_b128 v[204:207], v161 offset:3072
	ds_read_b128 v[208:211], v161 offset:4096
	ds_read_b128 v[212:215], v161 offset:5120
	ds_read_b128 v[216:219], v161 offset:6144
	ds_read_b128 v[220:223], v161 offset:7168
	s_waitcnt vmcnt(8)
	s_waitcnt lgkmcnt(0)
	s_barrier
	s_setprio 1
	s_waitcnt lgkmcnt(0)
	v_mfma_f32_16x16x32_bf16 v[126:129], v[130:133], v[180:183], v[126:129]
	v_mfma_f32_16x16x32_bf16 v[122:125], v[148:151], v[180:183], v[122:125]
	v_mfma_f32_16x16x32_bf16 v[110:113], v[130:133], v[188:191], v[110:113]
	v_mfma_f32_16x16x32_bf16 v[106:109], v[148:151], v[188:191], v[106:109]
	v_mfma_f32_16x16x32_bf16 v[94:97], v[130:133], v[208:211], v[94:97]
	v_mfma_f32_16x16x32_bf16 v[90:93], v[148:151], v[208:211], v[90:93]
	v_mfma_f32_16x16x32_bf16 v[78:81], v[130:133], v[216:219], v[78:81]
	v_mfma_f32_16x16x32_bf16 v[74:77], v[148:151], v[216:219], v[74:77]
	v_mfma_f32_16x16x32_bf16 v[126:129], v[134:137], v[184:187], v[126:129]
	v_mfma_f32_16x16x32_bf16 v[122:125], v[152:155], v[184:187], v[122:125]
	v_mfma_f32_16x16x32_bf16 v[110:113], v[134:137], v[204:207], v[110:113]
	v_mfma_f32_16x16x32_bf16 v[106:109], v[152:155], v[204:207], v[106:109]
	v_mfma_f32_16x16x32_bf16 v[94:97], v[134:137], v[212:215], v[94:97]
	v_mfma_f32_16x16x32_bf16 v[90:93], v[152:155], v[212:215], v[90:93]
	v_mfma_f32_16x16x32_bf16 v[78:81], v[134:137], v[220:223], v[78:81]
	v_mfma_f32_16x16x32_bf16 v[74:77], v[152:155], v[220:223], v[74:77]
	s_setprio 0
	s_setprio 1
	v_mfma_f32_16x16x32_bf16 v[118:121], v[164:167], v[180:183], v[118:121]
	v_mfma_f32_16x16x32_bf16 v[114:117], v[172:175], v[180:183], v[114:117]
	v_mfma_f32_16x16x32_bf16 v[102:105], v[164:167], v[188:191], v[102:105]
	v_mfma_f32_16x16x32_bf16 v[98:101], v[172:175], v[188:191], v[98:101]
	v_mfma_f32_16x16x32_bf16 v[86:89], v[164:167], v[208:211], v[86:89]
	v_mfma_f32_16x16x32_bf16 v[82:85], v[172:175], v[208:211], v[82:85]
	v_mfma_f32_16x16x32_bf16 v[70:73], v[164:167], v[216:219], v[70:73]
	v_mfma_f32_16x16x32_bf16 v[66:69], v[172:175], v[216:219], v[66:69]
	v_mfma_f32_16x16x32_bf16 v[118:121], v[168:171], v[184:187], v[118:121]
	v_mfma_f32_16x16x32_bf16 v[114:117], v[176:179], v[184:187], v[114:117]
	v_mfma_f32_16x16x32_bf16 v[102:105], v[168:171], v[204:207], v[102:105]
	v_mfma_f32_16x16x32_bf16 v[98:101], v[176:179], v[204:207], v[98:101]
	v_mfma_f32_16x16x32_bf16 v[86:89], v[168:171], v[212:215], v[86:89]
	v_mfma_f32_16x16x32_bf16 v[82:85], v[176:179], v[212:215], v[82:85]
	v_mfma_f32_16x16x32_bf16 v[70:73], v[168:171], v[220:223], v[70:73]
	v_mfma_f32_16x16x32_bf16 v[66:69], v[176:179], v[220:223], v[66:69]
	s_setprio 0
	s_barrier
	s_add_i32 s37, s37, s2
	v_lshl_add_u64 v[192:193], s[20:21], 0, v[0:1]
	s_mov_b32 m0, s37
	s_nop 0
	global_load_lds_dwordx4 v[192:193], off
	s_add_i32 m0, s37, 0x2000
	s_add_u32 s56, s20, 0x40000
	v_lshl_add_u64 v[194:195], s[20:21], 0, v[138:139]
	s_addc_u32 s57, s21, 0
	s_add_i32 s37, s58, s2
	global_load_lds_dwordx4 v[194:195], off
	v_lshl_add_u64 v[224:225], s[56:57], 0, v[0:1]
	s_mov_b32 m0, s37
	v_lshl_add_u64 v[226:227], s[50:51], 0, v[140:141]
	global_load_lds_dwordx4 v[224:225], off
	v_lshl_add_u64 v[224:225], s[56:57], 0, v[138:139]
	s_add_i32 m0, s37, 0x2000
	s_nop 0
	global_load_lds_dwordx4 v[224:225], off
	v_lshl_add_u64 v[224:225], s[50:51], 0, v[142:143]
	s_mov_b32 m0, s3
	s_nop 0
	global_load_lds_dwordx4 v[224:225], off
	s_mov_b32 m0, s16
	s_nop 0
	global_load_lds_dwordx4 v[226:227], off
	ds_read_b128 v[180:183], v161 offset:16384
	ds_read_b128 v[184:187], v161 offset:17408
	ds_read_b128 v[188:191], v161 offset:18432
	ds_read_b128 v[204:207], v161 offset:19456
	ds_read_b128 v[208:211], v161 offset:20480
	ds_read_b128 v[212:215], v161 offset:21504
	ds_read_b128 v[216:219], v161 offset:22528
	ds_read_b128 v[220:223], v161 offset:23552
	s_waitcnt vmcnt(8)
	s_waitcnt lgkmcnt(0)
	s_barrier
; #define PG8_STAGE(bufoff, gbase, voff) do { _Pragma("unroll") for (int _i = 0; _i < 2; ++_i) \
;         __builtin_amdgcn_global_load_lds((const unsigned*)((const char*)(gbase) + (voff)[_i]), (PG8_LAS unsigned*)(lds + (bufoff) + ldsw + _i * 8192), 16, 0, 0); } while (0)
; #define PG8_LDA(dst, b, h) do { _Pragma("unroll") for (int m = 0; m < 4; ++m) _Pragma("unroll") for (int k = 0; k < 2; ++k) dst[m][k] = *(const PG8_LAS bf16x8*)(lds + PG8_SA(b, h) + aoff + m * 2048 + k * 1024); } while (0)
; #define PG8_LDB(dst, b, h) do { _Pragma("unroll") for (int n = 0; n < 2; ++n) _Pragma("unroll") for (int k = 0; k < 2; ++k) dst[n][k] = *(const PG8_LAS bf16x8*)(lds + PG8_SB(b, h) + boff + n * 2048 + k * 1024); } while (0)
; #define PG8_MMA(ai, bj, At, Bt) do { __builtin_amdgcn_s_setprio(1); _Pragma("unroll") for (int m = 0; m < 4; ++m) _Pragma("unroll") for (int n = 0; n < 2; ++n) _Pragma("unroll") for (int k = 0; k < 2; ++k) \
;         acc[ai][bj][m][n] = __builtin_amdgcn_mfma_f32_16x16x32_bf16(Bt[n][k], At[m][k], acc[ai][bj][m][n], 0, 0, 0); __builtin_amdgcn_s_setprio(0); } while (0)
; #define PG8_WAIT_V(n) asm volatile("s_waitcnt vmcnt(" #n ")" ::: "memory")
; #define PG8_WAIT_L(n) asm volatile("s_waitcnt lgkmcnt(" #n ")" ::: "memory")
; #define PG8_BAR __builtin_amdgcn_s_barrier()
; #define PG8_SCHED __builtin_amdgcn_sched_barrier(0)
; template <class Epi, class Sched, bool ALIGN_EPI = false, bool SP2 = false>
; __device__ __forceinline__ void gemm_phase(PG8_LAS unsigned char* lds, const Gemm g, const Sched& S, const Epi& E) {
;     ...
;             PG8_WAIT_V(8); PG8_WAIT_L(0); PG8_BAR; PG8_MMA(1, 0, At, B0); PG8_MMA(1, 1, At, B1); PG8_BAR; PG8_SCHED;
;             PG8_LDB(B0, 1, 0); PG8_LDB(B1, 1, 1); PG8_SCHED; PG8_LDA(At, 1, 0); PG8_STAGE(PG8_SA(0, 1), a2 + hstep, voffA);
;             PG8_WAIT_V(8); PG8_WAIT_L(0); PG8_BAR; PG8_MMA(0, 0, At, B0); PG8_MMA(0, 1, At, B1); PG8_BAR; PG8_SCHED;
	s_setprio 1
	s_waitcnt lgkmcnt(0)
	v_mfma_f32_16x16x32_bf16 v[62:65], v[130:133], v[180:183], v[62:65]
	v_mfma_f32_16x16x32_bf16 v[58:61], v[148:151], v[180:183], v[58:61]
	v_mfma_f32_16x16x32_bf16 v[46:49], v[130:133], v[188:191], v[46:49]
	v_mfma_f32_16x16x32_bf16 v[42:45], v[148:151], v[188:191], v[42:45]
	v_mfma_f32_16x16x32_bf16 v[30:33], v[130:133], v[208:211], v[30:33]
	v_mfma_f32_16x16x32_bf16 v[26:29], v[148:151], v[208:211], v[26:29]
	v_mfma_f32_16x16x32_bf16 v[14:17], v[130:133], v[216:219], v[14:17]
	v_mfma_f32_16x16x32_bf16 v[10:13], v[148:151], v[216:219], v[10:13]
	v_mfma_f32_16x16x32_bf16 v[62:65], v[134:137], v[184:187], v[62:65]
	v_mfma_f32_16x16x32_bf16 v[58:61], v[152:155], v[184:187], v[58:61]
	v_mfma_f32_16x16x32_bf16 v[46:49], v[134:137], v[204:207], v[46:49]
	v_mfma_f32_16x16x32_bf16 v[42:45], v[152:155], v[204:207], v[42:45]
	v_mfma_f32_16x16x32_bf16 v[30:33], v[134:137], v[212:215], v[30:33]
	v_mfma_f32_16x16x32_bf16 v[26:29], v[152:155], v[212:215], v[26:29]
	v_mfma_f32_16x16x32_bf16 v[14:17], v[134:137], v[220:223], v[14:17]
	v_mfma_f32_16x16x32_bf16 v[10:13], v[152:155], v[220:223], v[10:13]
	s_setprio 0
	s_setprio 1
	v_mfma_f32_16x16x32_bf16 v[54:57], v[164:167], v[180:183], v[54:57]
	v_mfma_f32_16x16x32_bf16 v[50:53], v[172:175], v[180:183], v[50:53]
	v_mfma_f32_16x16x32_bf16 v[38:41], v[164:167], v[188:191], v[38:41]
	v_mfma_f32_16x16x32_bf16 v[34:37], v[172:175], v[188:191], v[34:37]
	v_mfma_f32_16x16x32_bf16 v[22:25], v[164:167], v[208:211], v[22:25]
	v_mfma_f32_16x16x32_bf16 v[18:21], v[172:175], v[208:211], v[18:21]
	v_mfma_f32_16x16x32_bf16 v[6:9], v[164:167], v[216:219], v[6:9]
	v_mfma_f32_16x16x32_bf16 v[2:5], v[172:175], v[216:219], v[2:5]
	v_mfma_f32_16x16x32_bf16 v[54:57], v[168:171], v[184:187], v[54:57]
	v_mfma_f32_16x16x32_bf16 v[50:53], v[176:179], v[184:187], v[50:53]
	v_mfma_f32_16x16x32_bf16 v[38:41], v[168:171], v[204:207], v[38:41]
	v_mfma_f32_16x16x32_bf16 v[34:37], v[176:179], v[204:207], v[34:37]
	v_mfma_f32_16x16x32_bf16 v[22:25], v[168:171], v[212:215], v[22:25]
	v_mfma_f32_16x16x32_bf16 v[18:21], v[176:179], v[212:215], v[18:21]
	v_mfma_f32_16x16x32_bf16 v[6:9], v[168:171], v[220:223], v[6:9]
	v_mfma_f32_16x16x32_bf16 v[2:5], v[176:179], v[220:223], v[2:5]
	s_setprio 0
	s_barrier
	s_add_i32 s37, 0, 0x18000
	s_add_i32 s56, 0, 0x1c000
	s_add_u32 s50, s50, 0x40000
	s_addc_u32 s51, s51, 0
	s_mov_b32 m0, s18
	v_lshl_add_u64 v[228:229], s[50:51], 0, v[142:143]
	global_load_lds_dwordx4 v[228:229], off
	v_lshl_add_u64 v[228:229], s[50:51], 0, v[140:141]
	s_mov_b32 m0, s19
	s_nop 0
	global_load_lds_dwordx4 v[228:229], off
	v_add_u32_e32 v152, s37, v157
	v_add_u32_e32 v163, s56, v157
	ds_read_b128 v[130:133], v152
	ds_read_b128 v[134:137], v152 offset:1024
	ds_read_b128 v[148:151], v152 offset:2048
	ds_read_b128 v[152:155], v152 offset:3072
	ds_read_b128 v[164:167], v163
	ds_read_b128 v[168:171], v163 offset:1024
	ds_read_b128 v[172:175], v163 offset:2048
	ds_read_b128 v[176:179], v163 offset:3072
	ds_read_b128 v[180:183], v161 offset:32768
	ds_read_b128 v[184:187], v161 offset:33792
	ds_read_b128 v[188:191], v161 offset:34816
	ds_read_b128 v[204:207], v161 offset:35840
	ds_read_b128 v[208:211], v161 offset:36864
	ds_read_b128 v[212:215], v161 offset:37888
	ds_read_b128 v[216:219], v161 offset:38912
	ds_read_b128 v[220:223], v161 offset:39936
	s_waitcnt vmcnt(8)
	s_waitcnt lgkmcnt(0)
	s_barrier
	s_setprio 1
	s_waitcnt lgkmcnt(0)
	v_mfma_f32_16x16x32_bf16 v[126:129], v[130:133], v[180:183], v[126:129]
	v_mfma_f32_16x16x32_bf16 v[122:125], v[148:151], v[180:183], v[122:125]
	v_mfma_f32_16x16x32_bf16 v[110:113], v[130:133], v[188:191], v[110:113]
	v_mfma_f32_16x16x32_bf16 v[106:109], v[148:151], v[188:191], v[106:109]
	v_mfma_f32_16x16x32_bf16 v[94:97], v[130:133], v[208:211], v[94:97]
	v_mfma_f32_16x16x32_bf16 v[90:93], v[148:151], v[208:211], v[90:93]
	v_mfma_f32_16x16x32_bf16 v[78:81], v[130:133], v[216:219], v[78:81]
	v_mfma_f32_16x16x32_bf16 v[74:77], v[148:151], v[216:219], v[74:77]
	v_mfma_f32_16x16x32_bf16 v[126:129], v[134:137], v[184:187], v[126:129]
	v_mfma_f32_16x16x32_bf16 v[122:125], v[152:155], v[184:187], v[122:125]
	v_mfma_f32_16x16x32_bf16 v[110:113], v[134:137], v[204:207], v[110:113]
	v_mfma_f32_16x16x32_bf16 v[106:109], v[152:155], v[204:207], v[106:109]
	v_mfma_f32_16x16x32_bf16 v[94:97], v[134:137], v[212:215], v[94:97]
	v_mfma_f32_16x16x32_bf16 v[90:93], v[152:155], v[212:215], v[90:93]
	v_mfma_f32_16x16x32_bf16 v[78:81], v[134:137], v[220:223], v[78:81]
	v_mfma_f32_16x16x32_bf16 v[74:77], v[152:155], v[220:223], v[74:77]
	s_setprio 0
	s_setprio 1
	v_mfma_f32_16x16x32_bf16 v[118:121], v[164:167], v[180:183], v[118:121]
	v_mfma_f32_16x16x32_bf16 v[114:117], v[172:175], v[180:183], v[114:117]
	v_mfma_f32_16x16x32_bf16 v[102:105], v[164:167], v[188:191], v[102:105]
	v_mfma_f32_16x16x32_bf16 v[98:101], v[172:175], v[188:191], v[98:101]
	v_mfma_f32_16x16x32_bf16 v[86:89], v[164:167], v[208:211], v[86:89]
	v_mfma_f32_16x16x32_bf16 v[82:85], v[172:175], v[208:211], v[82:85]
	v_mfma_f32_16x16x32_bf16 v[70:73], v[164:167], v[216:219], v[70:73]
	v_mfma_f32_16x16x32_bf16 v[66:69], v[172:175], v[216:219], v[66:69]
	v_mfma_f32_16x16x32_bf16 v[118:121], v[168:171], v[184:187], v[118:121]
	v_mfma_f32_16x16x32_bf16 v[114:117], v[176:179], v[184:187], v[114:117]
	v_mfma_f32_16x16x32_bf16 v[102:105], v[168:171], v[204:207], v[102:105]
	v_mfma_f32_16x16x32_bf16 v[98:101], v[176:179], v[204:207], v[98:101]
	v_mfma_f32_16x16x32_bf16 v[86:89], v[168:171], v[212:215], v[86:89]
	v_mfma_f32_16x16x32_bf16 v[82:85], v[176:179], v[212:215], v[82:85]
	v_mfma_f32_16x16x32_bf16 v[70:73], v[168:171], v[220:223], v[70:73]
	v_mfma_f32_16x16x32_bf16 v[66:69], v[176:179], v[220:223], v[66:69]
	s_setprio 0
	s_barrier
; #define PG8_STAGE(bufoff, gbase, voff) do { _Pragma("unroll") for (int _i = 0; _i < 2; ++_i) \
;         __builtin_amdgcn_global_load_lds((const unsigned*)((const char*)(gbase) + (voff)[_i]), (PG8_LAS unsigned*)(lds + (bufoff) + ldsw + _i * 8192), 16, 0, 0); } while (0)
; #define PG8_LDA(dst, b, h) do { _Pragma("unroll") for (int m = 0; m < 4; ++m) _Pragma("unroll") for (int k = 0; k < 2; ++k) dst[m][k] = *(const PG8_LAS bf16x8*)(lds + PG8_SA(b, h) + aoff + m * 2048 + k * 1024); } while (0)
; #define PG8_MMA(ai, bj, At, Bt) do { __builtin_amdgcn_s_setprio(1); _Pragma("unroll") for (int m = 0; m < 4; ++m) _Pragma("unroll") for (int n = 0; n < 2; ++n) _Pragma("unroll") for (int k = 0; k < 2; ++k) \
;         acc[ai][bj][m][n] = __builtin_amdgcn_mfma_f32_16x16x32_bf16(Bt[n][k], At[m][k], acc[ai][bj][m][n], 0, 0, 0); __builtin_amdgcn_s_setprio(0); } while (0)
; #define PG8_WAIT_V(n) asm volatile("s_waitcnt vmcnt(" #n ")" ::: "memory")
; #define PG8_WAIT_L(n) asm volatile("s_waitcnt lgkmcnt(" #n ")" ::: "memory")
; #define PG8_BAR __builtin_amdgcn_s_barrier()
; #define PG8_SCHED __builtin_amdgcn_sched_barrier(0)
; template <class Epi, class Sched, bool ALIGN_EPI = false, bool SP2 = false>
; __device__ __forceinline__ void gemm_phase(PG8_LAS unsigned char* lds, const Gemm g, const Sched& S, const Epi& E) {
;     ...
;             PG8_LDA(At, 1, 1); PG8_STAGE(PG8_SB(1, 0), b3, voffB); PG8_STAGE(PG8_SB(1, 1), b3 + hstep, voffB); PG8_STAGE(PG8_SA(1, 0), a3, voffA);
;             PG8_WAIT_V(8); PG8_WAIT_L(0); PG8_BAR; PG8_MMA(1, 0, At, B0); PG8_MMA(1, 1, At, B1); PG8_BAR; PG8_SCHED;
	s_add_i32 s37, s37, s2
	v_lshl_add_u64 v[192:193], v[192:193], 0, s[28:29]
	s_mov_b32 m0, s37
	s_nop 0
	global_load_lds_dwordx4 v[192:193], off
	s_add_i32 m0, s37, 0x2000
	s_add_u32 s20, s20, 0x40080
	v_lshl_add_u64 v[192:193], v[194:195], 0, s[28:29]
	s_addc_u32 s21, s21, 0
	s_add_i32 s37, s56, s2
	global_load_lds_dwordx4 v[192:193], off
	v_lshl_add_u64 v[192:193], s[20:21], 0, v[0:1]
	s_mov_b32 m0, s37
	s_nop 0
	global_load_lds_dwordx4 v[192:193], off
	v_lshl_add_u64 v[192:193], s[20:21], 0, v[138:139]
	s_add_i32 m0, s37, 0x2000
	s_nop 0
	global_load_lds_dwordx4 v[192:193], off
	v_lshl_add_u64 v[192:193], v[224:225], 0, s[28:29]
	s_mov_b32 m0, s33
	s_nop 0
	global_load_lds_dwordx4 v[192:193], off
	v_lshl_add_u64 v[192:193], v[226:227], 0, s[28:29]
	s_mov_b32 m0, s34
	s_nop 0
	global_load_lds_dwordx4 v[192:193], off
	ds_read_b128 v[180:183], v161 offset:49152
	ds_read_b128 v[184:187], v161 offset:50176
	ds_read_b128 v[188:191], v161 offset:51200
	ds_read_b128 v[204:207], v161 offset:52224
	ds_read_b128 v[208:211], v161 offset:53248
	ds_read_b128 v[212:215], v161 offset:54272
	ds_read_b128 v[216:219], v161 offset:55296
	ds_read_b128 v[220:223], v161 offset:56320
	s_waitcnt vmcnt(8)
	s_waitcnt lgkmcnt(0)
	s_barrier
	s_setprio 1
	s_waitcnt lgkmcnt(0)
	v_mfma_f32_16x16x32_bf16 v[62:65], v[130:133], v[180:183], v[62:65]
	v_mfma_f32_16x16x32_bf16 v[58:61], v[148:151], v[180:183], v[58:61]
	v_mfma_f32_16x16x32_bf16 v[46:49], v[130:133], v[188:191], v[46:49]
	v_mfma_f32_16x16x32_bf16 v[42:45], v[148:151], v[188:191], v[42:45]
	v_mfma_f32_16x16x32_bf16 v[30:33], v[130:133], v[208:211], v[30:33]
	v_mfma_f32_16x16x32_bf16 v[26:29], v[148:151], v[208:211], v[26:29]
	v_mfma_f32_16x16x32_bf16 v[14:17], v[130:133], v[216:219], v[14:17]
	v_mfma_f32_16x16x32_bf16 v[10:13], v[148:151], v[216:219], v[10:13]
	v_mfma_f32_16x16x32_bf16 v[62:65], v[134:137], v[184:187], v[62:65]
	v_mfma_f32_16x16x32_bf16 v[58:61], v[152:155], v[184:187], v[58:61]
	v_mfma_f32_16x16x32_bf16 v[46:49], v[134:137], v[204:207], v[46:49]
	v_mfma_f32_16x16x32_bf16 v[42:45], v[152:155], v[204:207], v[42:45]
	v_mfma_f32_16x16x32_bf16 v[30:33], v[134:137], v[212:215], v[30:33]
	v_mfma_f32_16x16x32_bf16 v[26:29], v[152:155], v[212:215], v[26:29]
	v_mfma_f32_16x16x32_bf16 v[14:17], v[134:137], v[220:223], v[14:17]
	v_mfma_f32_16x16x32_bf16 v[10:13], v[152:155], v[220:223], v[10:13]
	s_setprio 0
	s_setprio 1
	v_mfma_f32_16x16x32_bf16 v[54:57], v[164:167], v[180:183], v[54:57]
	v_mfma_f32_16x16x32_bf16 v[50:53], v[172:175], v[180:183], v[50:53]
	v_mfma_f32_16x16x32_bf16 v[38:41], v[164:167], v[188:191], v[38:41]
	v_mfma_f32_16x16x32_bf16 v[34:37], v[172:175], v[188:191], v[34:37]
	v_mfma_f32_16x16x32_bf16 v[22:25], v[164:167], v[208:211], v[22:25]
	v_mfma_f32_16x16x32_bf16 v[18:21], v[172:175], v[208:211], v[18:21]
	v_mfma_f32_16x16x32_bf16 v[6:9], v[164:167], v[216:219], v[6:9]
	v_mfma_f32_16x16x32_bf16 v[2:5], v[172:175], v[216:219], v[2:5]
	v_mfma_f32_16x16x32_bf16 v[54:57], v[168:171], v[184:187], v[54:57]
	v_mfma_f32_16x16x32_bf16 v[50:53], v[176:179], v[184:187], v[50:53]
	v_mfma_f32_16x16x32_bf16 v[38:41], v[168:171], v[204:207], v[38:41]
	v_mfma_f32_16x16x32_bf16 v[34:37], v[176:179], v[204:207], v[34:37]
	v_mfma_f32_16x16x32_bf16 v[22:25], v[168:171], v[212:215], v[22:25]
	v_mfma_f32_16x16x32_bf16 v[18:21], v[176:179], v[212:215], v[18:21]
	v_mfma_f32_16x16x32_bf16 v[6:9], v[168:171], v[220:223], v[6:9]
	v_mfma_f32_16x16x32_bf16 v[2:5], v[176:179], v[220:223], v[2:5]
	s_setprio 0
	s_barrier
	s_add_i32 s55, s55, 2
	s_add_u32 s8, s8, 0x100
	s_addc_u32 s9, s9, 0
	s_add_u32 s53, s53, 0x100
	s_addc_u32 s54, s54, 0
	s_cmp_gt_u32 s55, 13
	s_cbranch_scc0 .LBB0_918
	s_and_b64 vcc, exec, s[4:5]
	s_cbranch_vccz .LBB0_921
	s_barrier
